# stacked: hyena middle pass rewritten (16 LDS reads up front, 2-op complex multiplies) and two redundant workgroup barriers dropped, on top of v25
# speedup vs baseline: 1.0171x; 1.0008x over previous
; #define LAS __attribute__((address_space(3)))
; __device__ __forceinline__ f32x2 cmul(f32x2 a, f32x2 b) { return (f32x2){a.x * b.x - a.y * b.y, a.x * b.y + a.y * b.x}; }
; template <bool INV> __device__ __forceinline__ void bfly16_tab(f32x2 (&x)[16], const LAS f32x2* T, int tstride, int j) {
;     if (INV) {
; #pragma unroll
;         for (int q = 1; q < 16; ++q) { f32x2 p = T[q * tstride + j]; p.y = -p.y; x[q] = cmul(x[q], p); } }
;     dft16<INV>(x);
;     if (!INV) {
; #pragma unroll
;         for (int r = 1; r < 16; ++r) { const f32x2 p = T[r * tstride + j]; x[4 * (r & 3) + (r >> 2)] = cmul(x[4 * (r & 3) + (r >> 2)], p); } }
; }
; template <bool INV> __device__ __forceinline__ void pass16_s4(LAS f32x2* X, const LAS f32x2* TH, const LAS f32x2* TL, int tid) {
; #pragma unroll 1
;     for (int s = 0; s < 2; ++s) {
;         const int b = tid + NTHR * s, blk = b >> 2, jj = b & 3;
;         LAS f32x2* P = X + blk * 68 + jj;
;         f32x2 x[16];
; #pragma unroll
;         for (int q = 0; q < 16; ++q) x[q] = P[4 * q];
;         bfly16_tab<INV>(x, TH - 1024, 4, jj);
; #pragma unroll
;         for (int c = 0; c < 4; ++c)
; #pragma unroll
;             for (int d = 0; d < 4; ++d) P[4 * (c + 4 * d)] = x[4 * c + d];
;     }
; }
.LBB0_700:
	v_add_u32_e32 v128, s0, v140
	v_lshrrev_b32_e32 v147, 2, v128
	v_mad_u32_u24 v151, v147, s43, v144
	ds_read_b64 v[0:1], v151 offset:0
	ds_read_b64 v[2:3], v151 offset:256
	ds_read_b64 v[4:5], v151 offset:32
	ds_read_b64 v[6:7], v151 offset:288
	ds_read_b64 v[8:9], v151 offset:64
	ds_read_b64 v[10:11], v151 offset:320
	ds_read_b64 v[12:13], v151 offset:96
	ds_read_b64 v[14:15], v151 offset:352
	ds_read_b64 v[16:17], v151 offset:128
	ds_read_b64 v[18:19], v151 offset:384
	ds_read_b64 v[20:21], v151 offset:160
	ds_read_b64 v[22:23], v151 offset:416
	ds_read_b64 v[24:25], v151 offset:192
	ds_read_b64 v[26:27], v151 offset:448
	ds_read_b64 v[28:29], v151 offset:224
	ds_read_b64 v[30:31], v151 offset:480
	s_cmp_eq_u32 s0, 0
	s_movk_i32 s0, 0x200
	s_mov_b64 s[36:37], 0
	s_waitcnt lgkmcnt(14)
	v_pk_add_f32 v[32:33], v[0:1], v[2:3]
	s_waitcnt lgkmcnt(12)
	v_pk_add_f32 v[34:35], v[4:5], v[6:7]
	s_waitcnt lgkmcnt(10)
	v_pk_add_f32 v[36:37], v[8:9], v[10:11]
	s_waitcnt lgkmcnt(8)
	v_pk_add_f32 v[38:39], v[12:13], v[14:15]
	v_pk_add_f32 v[2:3], v[0:1], v[2:3] neg_lo:[0,1] neg_hi:[0,1]
	v_pk_add_f32 v[4:5], v[4:5], v[6:7] neg_lo:[0,1] neg_hi:[0,1]
	v_pk_add_f32 v[10:11], v[8:9], v[10:11] neg_lo:[0,1] neg_hi:[0,1]
	v_pk_add_f32 v[12:13], v[12:13], v[14:15] neg_lo:[0,1] neg_hi:[0,1]
	s_waitcnt lgkmcnt(6)
	v_pk_add_f32 v[14:15], v[16:17], v[18:19]
	s_waitcnt lgkmcnt(4)
	v_pk_add_f32 v[8:9], v[20:21], v[22:23]
	s_waitcnt lgkmcnt(2)
	v_pk_add_f32 v[6:7], v[24:25], v[26:27]
	s_waitcnt lgkmcnt(0)
	v_pk_add_f32 v[0:1], v[28:29], v[30:31]
	v_pk_add_f32 v[16:17], v[16:17], v[18:19] neg_lo:[0,1] neg_hi:[0,1]
	v_pk_add_f32 v[22:23], v[20:21], v[22:23] neg_lo:[0,1] neg_hi:[0,1]
	v_pk_add_f32 v[26:27], v[24:25], v[26:27] neg_lo:[0,1] neg_hi:[0,1]
	v_pk_add_f32 v[30:31], v[28:29], v[30:31] neg_lo:[0,1] neg_hi:[0,1]
	v_pk_add_f32 v[28:29], v[32:33], v[14:15]
	v_pk_add_f32 v[24:25], v[34:35], v[8:9]
	v_pk_add_f32 v[20:21], v[36:37], v[6:7]
	v_pk_add_f32 v[18:19], v[38:39], v[0:1]
	v_pk_add_f32 v[32:33], v[32:33], v[14:15] neg_lo:[0,1] neg_hi:[0,1]
	v_pk_add_f32 v[34:35], v[34:35], v[8:9] neg_lo:[0,1] neg_hi:[0,1]
	v_pk_add_f32 v[6:7], v[36:37], v[6:7] neg_lo:[0,1] neg_hi:[0,1]
	v_pk_add_f32 v[0:1], v[38:39], v[0:1] neg_lo:[0,1] neg_hi:[0,1]
	v_pk_add_f32 v[38:39], v[2:3], v[16:17] op_sel:[0,1] op_sel_hi:[1,0] neg_hi:[0,1]
	v_pk_add_f32 v[36:37], v[4:5], v[22:23] op_sel:[0,1] op_sel_hi:[1,0] neg_hi:[0,1]
	v_pk_add_f32 v[8:9], v[10:11], v[26:27] op_sel:[0,1] op_sel_hi:[1,0] neg_hi:[0,1]
	v_pk_add_f32 v[14:15], v[12:13], v[30:31] op_sel:[0,1] op_sel_hi:[1,0] neg_hi:[0,1]
	v_pk_add_f32 v[16:17], v[2:3], v[16:17] op_sel:[0,1] op_sel_hi:[1,0] neg_lo:[0,1]
	v_pk_add_f32 v[4:5], v[4:5], v[22:23] op_sel:[0,1] op_sel_hi:[1,0] neg_lo:[0,1]
	v_pk_add_f32 v[26:27], v[10:11], v[26:27] op_sel:[0,1] op_sel_hi:[1,0] neg_lo:[0,1]
	v_pk_add_f32 v[30:31], v[12:13], v[30:31] op_sel:[0,1] op_sel_hi:[1,0] neg_lo:[0,1]
	v_pk_mul_f32 v[12:13], v[36:37], s[70:71] op_sel_hi:[1,0]
	v_pk_mul_f32 v[10:11], v[34:35], s[72:73] op_sel_hi:[1,0]
	v_pk_mul_f32 v[22:23], v[4:5], s[64:65] op_sel_hi:[1,0]
	v_pk_mul_f32 v[2:3], v[8:9], s[72:73] op_sel_hi:[1,0]
	v_pk_mul_f32 v[40:41], v[26:27], s[72:73] op_sel_hi:[1,0]
	v_pk_mul_f32 v[42:43], v[14:15], s[64:65] op_sel_hi:[1,0]
	v_pk_mul_f32 v[44:45], v[0:1], s[72:73] op_sel_hi:[1,0]
	v_pk_mul_f32 v[46:47], v[30:31], s[82:83] op_sel_hi:[1,0]
	v_pk_fma_f32 v[36:37], v[36:37], s[44:45], v[12:13] op_sel:[0,0,1] op_sel_hi:[1,0,0] neg_lo:[0,0,1]
	v_pk_fma_f32 v[34:35], v[34:35], s[76:77], v[10:11] op_sel:[0,0,1] op_sel_hi:[1,0,0] neg_lo:[0,0,1]
	v_pk_fma_f32 v[4:5], v[4:5], s[82:83], v[22:23] op_sel:[0,0,1] op_sel_hi:[1,0,0] neg_lo:[0,0,1]
	v_pk_fma_f32 v[2:3], v[8:9], s[76:77], v[2:3] op_sel:[0,0,1] op_sel_hi:[1,0,0] neg_lo:[0,0,1]
	v_pk_fma_f32 v[26:27], v[26:27], s[72:73], v[40:41] op_sel:[0,0,1] op_sel_hi:[1,0,0] neg_lo:[0,0,1]
	v_pk_fma_f32 v[42:43], v[14:15], s[82:83], v[42:43] op_sel:[0,0,1] op_sel_hi:[1,0,0] neg_lo:[0,0,1]
	v_pk_fma_f32 v[44:45], v[0:1], s[72:73], v[44:45] op_sel:[0,0,1] op_sel_hi:[1,0,0] neg_lo:[0,0,1]
	v_pk_fma_f32 v[46:47], v[30:31], s[64:65], v[46:47] op_sel:[0,0,1] op_sel_hi:[1,0,0] neg_lo:[0,0,1]
	v_pk_add_f32 v[30:31], v[28:29], v[20:21]
	v_pk_add_f32 v[0:1], v[38:39], v[2:3]
	v_pk_add_f32 v[14:15], v[32:33], v[6:7] op_sel:[0,1] op_sel_hi:[1,0] neg_hi:[0,1]
	v_pk_add_f32 v[40:41], v[16:17], v[26:27]
	v_pk_add_f32 v[20:21], v[28:29], v[20:21] neg_lo:[0,1] neg_hi:[0,1]
	v_pk_add_f32 v[38:39], v[38:39], v[2:3] neg_lo:[0,1] neg_hi:[0,1]
	v_pk_add_f32 v[6:7], v[32:33], v[6:7] op_sel:[0,1] op_sel_hi:[1,0] neg_lo:[0,1]
	v_pk_add_f32 v[26:27], v[16:17], v[26:27] neg_lo:[0,1] neg_hi:[0,1]
	v_pk_add_f32 v[16:17], v[24:25], v[18:19]
	v_pk_add_f32 v[32:33], v[36:37], v[42:43]
	v_pk_add_f32 v[2:3], v[34:35], v[44:45]
	v_pk_add_f32 v[28:29], v[4:5], v[46:47]
	v_pk_add_f32 v[18:19], v[24:25], v[18:19] neg_lo:[0,1] neg_hi:[0,1]
	v_pk_add_f32 v[36:37], v[36:37], v[42:43] neg_lo:[0,1] neg_hi:[0,1]
	v_pk_add_f32 v[34:35], v[34:35], v[44:45] neg_lo:[0,1] neg_hi:[0,1]
	v_pk_add_f32 v[4:5], v[4:5], v[46:47] neg_lo:[0,1] neg_hi:[0,1]
	v_pk_add_f32 v[46:47], v[30:31], v[16:17]
	v_pk_add_f32 v[44:45], v[0:1], v[32:33]
	v_pk_add_f32 v[42:43], v[14:15], v[2:3]
	v_pk_add_f32 v[24:25], v[40:41], v[28:29]
	v_pk_add_f32 v[16:17], v[30:31], v[16:17] neg_lo:[0,1] neg_hi:[0,1]
	v_pk_add_f32 v[32:33], v[0:1], v[32:33] neg_lo:[0,1] neg_hi:[0,1]
	v_pk_add_f32 v[2:3], v[14:15], v[2:3] neg_lo:[0,1] neg_hi:[0,1]
	v_pk_add_f32 v[28:29], v[40:41], v[28:29] neg_lo:[0,1] neg_hi:[0,1]
	v_pk_add_f32 v[40:41], v[20:21], v[18:19] op_sel:[0,1] op_sel_hi:[1,0] neg_hi:[0,1]
; #define LAS __attribute__((address_space(3)))
; template <bool INV> __device__ __forceinline__ void pass16_s4(LAS f32x2* X, const LAS f32x2* TH, const LAS f32x2* TL, int tid) {
; #pragma unroll 1
;     for (int s = 0; s < 2; ++s) {
;         const int b = tid + NTHR * s, blk = b >> 2, jj = b & 3;
;         LAS f32x2* P = X + blk * 68 + jj;
;         f32x2 x[16];
; #pragma unroll
;         for (int q = 0; q < 16; ++q) x[q] = P[4 * q];
;         bfly16_tab<INV>(x, TH - 1024, 4, jj);
; #pragma unroll
;         for (int c = 0; c < 4; ++c)
; #pragma unroll
;             for (int d = 0; d < 4; ++d) P[4 * (c + 4 * d)] = x[4 * c + d];
;     }
; }
; __device__ __forceinline__ void hyena_latent(Frame& F, int l, int ch, LAS f32x2* X, const LAS f32x2* TH, const LAS f32x2* TL, GAS f32x2* KS, const LAS float* CT  , bool wr = true) {
;     ...
; #pragma unroll
;             for (int i = 0; i < 8; ++i) { const int b = LT() + NTHR * i; const LAS f32x4* P = (const LAS f32x4*)(X + 4 * b + ((b >> 4) << 2)); const f32x4 u = P[0], v = P[1];
;                 f32x2 x0 = {u.x, u.y}, x1 = {u.z, u.w}, x2 = {v.x, v.y}, x3 = {v.z, v.w}; r4<false>(x0, x1, x2, x3);
;                 kreg[2 * i] = (f32x4){x0.x, x0.y, x1.x, x1.y}; kreg[2 * i + 1] = (f32x4){x2.x, x2.y, x3.x, x3.y}; }
;             LDS_BARRIER();
;             HP_END(31) }
;             { HP_BEGIN(32)
; #pragma unroll
;             for (int i = 0; i < 8; ++i) { const int g = LT() + NTHR * i, n0 = 4 * g;
;                 f32x4 z0 = pc0[i], z1 = pc1[i];
;                 if (o == 0) { const f32x4 c = pc0[i], d = pc1[i]; const int ln = F.lane;
;                     float l0 = lane_read(c.w, ln - 1), r0 = lane_read(c.x, ln + 1), l1 = lane_read(d.w, ln - 1), r1 = lane_read(d.x, ln + 1);
;                     if (ln == 0) { l0 = n0 > 0 ? hv[n0 - 1] : 0.f; l1 = n0 > 0 ? hv[SEQ + n0 - 1] : 0.f; }
;                     if (ln == 63) { r0 = n0 + 4 < SEQ ? hv[n0 + 4] : 0.f; r1 = n0 + 4 < SEQ ? hv[SEQ + n0 + 4] : 0.f; }
;                     z0 = (f32x4){vw0 * l0 + vw1 * c.x + vw2 * c.y + vbb, vw0 * c.x + vw1 * c.y + vw2 * c.z + vbb, vw0 * c.y + vw1 * c.z + vw2 * c.w + vbb, vw0 * c.z + vw1 * c.w + vw2 * r0 + vbb};
;                     z1 = (f32x4){vw0 * l1 + vw1 * d.x + vw2 * d.y + vbb, vw0 * d.x + vw1 * d.y + vw2 * d.z + vbb, vw0 * d.y + vw1 * d.z + vw2 * d.w + vbb, vw0 * d.z + vw1 * d.w + vw2 * r1 + vbb}; }
	v_pk_add_f32 v[14:15], v[38:39], v[36:37] op_sel:[0,1] op_sel_hi:[1,0] neg_hi:[0,1]
	v_pk_add_f32 v[0:1], v[6:7], v[34:35] op_sel:[0,1] op_sel_hi:[1,0] neg_hi:[0,1]
	v_pk_add_f32 v[30:31], v[26:27], v[4:5] op_sel:[0,1] op_sel_hi:[1,0] neg_hi:[0,1]
	v_pk_add_f32 v[20:21], v[20:21], v[18:19] op_sel:[0,1] op_sel_hi:[1,0] neg_lo:[0,1]
	v_pk_add_f32 v[38:39], v[38:39], v[36:37] op_sel:[0,1] op_sel_hi:[1,0] neg_lo:[0,1]
	v_pk_add_f32 v[6:7], v[6:7], v[34:35] op_sel:[0,1] op_sel_hi:[1,0] neg_lo:[0,1]
	v_pk_add_f32 v[26:27], v[26:27], v[4:5] op_sel:[0,1] op_sel_hi:[1,0] neg_lo:[0,1]
	v_pk_mul_f32 v[4:5], v[44:45], v[232:233] op_sel:[0,1] op_sel_hi:[1,1]
	v_pk_mul_f32 v[34:35], v[42:43], v[234:235] op_sel:[0,1] op_sel_hi:[1,1]
	v_pk_fma_f32 v[4:5], v[44:45], v[232:233], v[4:5] op_sel:[0,0,1] op_sel_hi:[1,0,0] neg_lo:[0,0,1]
	v_pk_mul_f32 v[44:45], v[24:25], v[208:209] op_sel:[0,1] op_sel_hi:[1,1]
	v_pk_fma_f32 v[34:35], v[42:43], v[234:235], v[34:35] op_sel:[0,0,1] op_sel_hi:[1,0,0] neg_lo:[0,0,1]
	v_pk_mul_f32 v[42:43], v[40:41], v[210:211] op_sel:[0,1] op_sel_hi:[1,1]
	v_pk_fma_f32 v[44:45], v[24:25], v[208:209], v[44:45] op_sel:[0,0,1] op_sel_hi:[1,0,0] neg_lo:[0,0,1]
	v_pk_mul_f32 v[24:25], v[14:15], v[204:205] op_sel:[0,1] op_sel_hi:[1,1]
	v_pk_fma_f32 v[40:41], v[40:41], v[210:211], v[42:43] op_sel:[0,0,1] op_sel_hi:[1,0,0] neg_lo:[0,0,1]
	v_pk_mul_f32 v[42:43], v[0:1], v[206:207] op_sel:[0,1] op_sel_hi:[1,1]
	v_pk_fma_f32 v[14:15], v[14:15], v[204:205], v[24:25] op_sel:[0,0,1] op_sel_hi:[1,0,0] neg_lo:[0,0,1]
	v_pk_mul_f32 v[24:25], v[30:31], v[200:201] op_sel:[0,1] op_sel_hi:[1,1]
	v_pk_fma_f32 v[42:43], v[0:1], v[206:207], v[42:43] op_sel:[0,0,1] op_sel_hi:[1,0,0] neg_lo:[0,0,1]
	v_pk_mul_f32 v[0:1], v[16:17], v[202:203] op_sel:[0,1] op_sel_hi:[1,1]
	v_pk_fma_f32 v[30:31], v[30:31], v[200:201], v[24:25] op_sel:[0,0,1] op_sel_hi:[1,0,0] neg_lo:[0,0,1]
	v_pk_mul_f32 v[24:25], v[32:33], v[196:197] op_sel:[0,1] op_sel_hi:[1,1]
	v_pk_fma_f32 v[16:17], v[16:17], v[202:203], v[0:1] op_sel:[0,0,1] op_sel_hi:[1,0,0] neg_lo:[0,0,1]
	v_pk_mul_f32 v[0:1], v[2:3], v[198:199] op_sel:[0,1] op_sel_hi:[1,1]
	v_pk_fma_f32 v[32:33], v[32:33], v[196:197], v[24:25] op_sel:[0,0,1] op_sel_hi:[1,0,0] neg_lo:[0,0,1]
	v_pk_mul_f32 v[24:25], v[28:29], v[192:193] op_sel:[0,1] op_sel_hi:[1,1]
	v_pk_fma_f32 v[2:3], v[2:3], v[198:199], v[0:1] op_sel:[0,0,1] op_sel_hi:[1,0,0] neg_lo:[0,0,1]
	v_pk_mul_f32 v[0:1], v[20:21], v[194:195] op_sel:[0,1] op_sel_hi:[1,1]
	v_pk_fma_f32 v[28:29], v[28:29], v[192:193], v[24:25] op_sel:[0,0,1] op_sel_hi:[1,0,0] neg_lo:[0,0,1]
	v_pk_mul_f32 v[24:25], v[38:39], v[188:189] op_sel:[0,1] op_sel_hi:[1,1]
	v_pk_fma_f32 v[0:1], v[20:21], v[194:195], v[0:1] op_sel:[0,0,1] op_sel_hi:[1,0,0] neg_lo:[0,0,1]
	v_pk_mul_f32 v[20:21], v[6:7], v[190:191] op_sel:[0,1] op_sel_hi:[1,1]
	v_pk_fma_f32 v[38:39], v[38:39], v[188:189], v[24:25] op_sel:[0,0,1] op_sel_hi:[1,0,0] neg_lo:[0,0,1]
	v_pk_mul_f32 v[24:25], v[26:27], v[186:187] op_sel:[0,1] op_sel_hi:[1,1]
	v_pk_fma_f32 v[20:21], v[6:7], v[190:191], v[20:21] op_sel:[0,0,1] op_sel_hi:[1,0,0] neg_lo:[0,0,1]
	v_pk_fma_f32 v[26:27], v[26:27], v[186:187], v[24:25] op_sel:[0,0,1] op_sel_hi:[1,0,0] neg_lo:[0,0,1]
	ds_write_b64 v151, v[46:47] offset:0
	ds_write_b64 v151, v[4:5] offset:32
	ds_write_b64 v151, v[34:35] offset:64
	ds_write_b64 v151, v[44:45] offset:96
	ds_write_b64 v151, v[40:41] offset:128
	ds_write_b64 v151, v[14:15] offset:160
	ds_write_b64 v151, v[42:43] offset:192
	ds_write_b64 v151, v[30:31] offset:224
	ds_write_b64 v151, v[16:17] offset:256
	ds_write_b64 v151, v[32:33] offset:288
	ds_write_b64 v151, v[2:3] offset:320
	ds_write_b64 v151, v[28:29] offset:352
	ds_write_b64 v151, v[0:1] offset:384
	ds_write_b64 v151, v[38:39] offset:416
	ds_write_b64 v151, v[20:21] offset:448
	ds_write_b64 v151, v[26:27] offset:480
	s_cbranch_scc1 .LBB0_700
	v_mov_b32_e32 v0, v140
	s_waitcnt lgkmcnt(0)
	s_barrier
	v_mov_b32_e32 v128, v140
	v_lshlrev_b32_e32 v1, 5, v0
	v_lshlrev_b32_e32 v0, 1, v0
	v_and_b32_e32 v0, 0xffffffe0, v0
	v_add3_u32 v0, 0, v1, v0
	ds_read_b128 v[56:59], v0
	ds_read_b128 v[60:63], v0 offset:16
	v_mov_b32_e32 v0, v140
	s_and_b64 vcc, s[26:27], exec
	v_add_u32_e32 v0, 0x200, v0
	v_lshlrev_b32_e32 v1, 5, v0
	v_lshlrev_b32_e32 v0, 1, v0
	v_and_b32_e32 v0, 0xffffffe0, v0
	v_add3_u32 v0, 0, v1, v0
	ds_read_b128 v[48:51], v0
	ds_read_b128 v[52:55], v0 offset:16
	v_mov_b32_e32 v0, v140
	s_nop 0
	v_add_u32_e32 v0, 0x400, v0
	v_lshlrev_b32_e32 v1, 5, v0
	v_lshlrev_b32_e32 v0, 1, v0
	v_and_b32_e32 v0, 0xffffffe0, v0
	v_add3_u32 v0, 0, v1, v0
	ds_read_b128 v[40:43], v0
	ds_read_b128 v[44:47], v0 offset:16
	v_mov_b32_e32 v0, v140
	s_nop 0
	v_add_u32_e32 v0, 0x600, v0
	v_lshlrev_b32_e32 v1, 5, v0
	v_lshlrev_b32_e32 v0, 1, v0
	v_and_b32_e32 v0, 0xffffffe0, v0
	v_add3_u32 v0, 0, v1, v0
	ds_read_b128 v[32:35], v0
	ds_read_b128 v[36:39], v0 offset:16
	v_mov_b32_e32 v0, v140
	s_nop 0
	v_add_u32_e32 v0, 0x800, v0
	v_lshlrev_b32_e32 v1, 5, v0
	v_lshlrev_b32_e32 v0, 1, v0
	v_and_b32_e32 v0, 0xffffffe0, v0
	v_add3_u32 v0, 0, v1, v0
	ds_read_b128 v[24:27], v0
	ds_read_b128 v[28:31], v0 offset:16
	v_mov_b32_e32 v0, v140
	s_nop 0
	v_add_u32_e32 v0, 0xa00, v0
	v_lshlrev_b32_e32 v1, 5, v0
	v_lshlrev_b32_e32 v0, 1, v0
	v_and_b32_e32 v0, 0xffffffe0, v0
	v_add3_u32 v0, 0, v1, v0
	ds_read_b128 v[12:15], v0
	ds_read_b128 v[20:23], v0 offset:16
	v_mov_b32_e32 v0, v140
	s_nop 0
	v_add_u32_e32 v0, 0xc00, v0
	v_lshlrev_b32_e32 v1, 5, v0
	v_lshlrev_b32_e32 v0, 1, v0
	v_and_b32_e32 v0, 0xffffffe0, v0
	v_add3_u32 v0, 0, v1, v0
	ds_read_b128 v[4:7], v0
	ds_read_b128 v[16:19], v0 offset:16
	v_mov_b32_e32 v0, v140
	s_nop 0
	v_add_u32_e32 v0, 0xe00, v0
	v_lshlrev_b32_e32 v1, 5, v0
	v_lshlrev_b32_e32 v0, 1, v0
	v_and_b32_e32 v0, 0xffffffe0, v0
	v_add3_u32 v8, 0, v1, v0
	ds_read_b128 v[0:3], v8
	ds_read_b128 v[8:11], v8 offset:16
	s_waitcnt lgkmcnt(0)
	s_nop 0
	s_nop 0
	v_lshlrev_b32_e32 v176, 2, v128
	s_cbranch_vccz .LBB0_715
	s_waitcnt vmcnt(15)
	ds_bpermute_b32 v134, v143, v127
	ds_bpermute_b32 v133, v145, v124
	s_waitcnt vmcnt(14)
	ds_bpermute_b32 v130, v143, v123
	ds_bpermute_b32 v129, v145, v120
	s_and_saveexec_b64 s[36:37], s[8:9]
	s_cbranch_execz .LBB0_708
	v_cmp_lt_i32_e32 vcc, 0, v176
	s_waitcnt lgkmcnt(1)
	v_mov_b32_e32 v130, 0
	v_mov_b32_e32 v134, 0
	s_and_saveexec_b64 s[38:39], vcc
	s_cbranch_execz .LBB0_705
	v_lshl_add_u64 v[134:135], v[176:177], 2, s[20:21]
	global_load_dword v134, v[134:135], off offset:-4

; #define LAS __attribute__((address_space(3)))
; __device__ __forceinline__ f32x2 cmul(f32x2 a, f32x2 b) { return (f32x2){a.x * b.x - a.y * b.y, a.x * b.y + a.y * b.x}; }
; template <bool INV> __device__ __forceinline__ void dft16(f32x2 (&x)[16]) {
; #pragma unroll
;     for (int b = 0; b < 4; ++b) r4<INV>(x[b], x[4 + b], x[8 + b], x[12 + b]);
;     const float sg = INV ? -1.f : 1.f;
;     const f32x2 W1 = {0.92387953251f, -0.38268343236f * sg}, W2 = {0.70710678118f, -0.70710678118f * sg}, W3 = {0.38268343236f, -0.92387953251f * sg},
;                 W4 = {0.f, -1.f * sg}, W6 = {-0.70710678118f, -0.70710678118f * sg}, W9 = {-0.92387953251f, 0.38268343236f * sg};
;     x[5] = cmul(x[5], W1); x[9] = cmul(x[9], W2); x[13] = cmul(x[13], W3);
;     x[6] = cmul(x[6], W2); x[10] = cmul(x[10], W4); x[14] = cmul(x[14], W6);
;     x[7] = cmul(x[7], W3); x[11] = cmul(x[11], W6); x[15] = cmul(x[15], W9);
; #pragma unroll
;     for (int c = 0; c < 4; ++c) r4<INV>(x[4 * c], x[4 * c + 1], x[4 * c + 2], x[4 * c + 3]);
; }
; template <bool INV> __device__ __forceinline__ void pass16_s4(LAS f32x2* X, const LAS f32x2* TH, const LAS f32x2* TL, int tid) {
; #pragma unroll 1
;     for (int s = 0; s < 2; ++s) {
;         const int b = tid + NTHR * s, blk = b >> 2, jj = b & 3;
;         LAS f32x2* P = X + blk * 68 + jj;
;         f32x2 x[16];
; #pragma unroll
;         for (int q = 0; q < 16; ++q) x[q] = P[4 * q];
;         bfly16_tab<INV>(x, TH - 1024, 4, jj);
; #pragma unroll
;         for (int c = 0; c < 4; ++c)
; #pragma unroll
;             for (int d = 0; d < 4; ++d) P[4 * (c + 4 * d)] = x[4 * c + d];
;     }
; }
.LBB0_850:
	v_add_u32_e32 v128, s0, v140
	v_lshrrev_b32_e32 v147, 2, v128
	v_mad_u32_u24 v151, v147, s43, v144
	ds_read_b64 v[64:65], v151 offset:0
	ds_read_b64 v[66:67], v151 offset:256
	ds_read_b64 v[68:69], v151 offset:32
	ds_read_b64 v[70:71], v151 offset:288
	ds_read_b64 v[72:73], v151 offset:64
	ds_read_b64 v[74:75], v151 offset:320
	ds_read_b64 v[76:77], v151 offset:96
	ds_read_b64 v[78:79], v151 offset:352
	ds_read_b64 v[80:81], v151 offset:128
	ds_read_b64 v[82:83], v151 offset:384
	ds_read_b64 v[84:85], v151 offset:160
	ds_read_b64 v[86:87], v151 offset:416
	ds_read_b64 v[88:89], v151 offset:192
	ds_read_b64 v[90:91], v151 offset:448
	ds_read_b64 v[92:93], v151 offset:224
	ds_read_b64 v[94:95], v151 offset:480
	s_cmp_eq_u32 s0, 0
	s_movk_i32 s0, 0x200
	s_mov_b64 s[12:13], 0
	s_waitcnt lgkmcnt(14)
	v_pk_add_f32 v[96:97], v[64:65], v[66:67]
	s_waitcnt lgkmcnt(12)
	v_pk_add_f32 v[98:99], v[68:69], v[70:71]
	s_waitcnt lgkmcnt(10)
	v_pk_add_f32 v[100:101], v[72:73], v[74:75]
	s_waitcnt lgkmcnt(8)
	v_pk_add_f32 v[102:103], v[76:77], v[78:79]
	v_pk_add_f32 v[64:65], v[64:65], v[66:67] neg_lo:[0,1] neg_hi:[0,1]
	v_pk_add_f32 v[70:71], v[68:69], v[70:71] neg_lo:[0,1] neg_hi:[0,1]
	v_pk_add_f32 v[72:73], v[72:73], v[74:75] neg_lo:[0,1] neg_hi:[0,1]
	v_pk_add_f32 v[78:79], v[76:77], v[78:79] neg_lo:[0,1] neg_hi:[0,1]
	s_waitcnt lgkmcnt(6)
	v_pk_add_f32 v[76:77], v[80:81], v[82:83]
	s_waitcnt lgkmcnt(4)
	v_pk_add_f32 v[74:75], v[84:85], v[86:87]
	s_waitcnt lgkmcnt(2)
	v_pk_add_f32 v[68:69], v[88:89], v[90:91]
	s_waitcnt lgkmcnt(0)
	v_pk_add_f32 v[66:67], v[92:93], v[94:95]
	v_pk_add_f32 v[80:81], v[80:81], v[82:83] neg_lo:[0,1] neg_hi:[0,1]
	v_pk_add_f32 v[84:85], v[84:85], v[86:87] neg_lo:[0,1] neg_hi:[0,1]
	v_pk_add_f32 v[88:89], v[88:89], v[90:91] neg_lo:[0,1] neg_hi:[0,1]
	v_pk_add_f32 v[92:93], v[92:93], v[94:95] neg_lo:[0,1] neg_hi:[0,1]
	v_pk_add_f32 v[94:95], v[96:97], v[76:77]
	v_pk_add_f32 v[90:91], v[98:99], v[74:75]
	v_pk_add_f32 v[86:87], v[100:101], v[68:69]
	v_pk_add_f32 v[82:83], v[102:103], v[66:67]
	v_pk_add_f32 v[96:97], v[96:97], v[76:77] neg_lo:[0,1] neg_hi:[0,1]
	v_pk_add_f32 v[74:75], v[98:99], v[74:75] neg_lo:[0,1] neg_hi:[0,1]
	v_pk_add_f32 v[100:101], v[100:101], v[68:69] neg_lo:[0,1] neg_hi:[0,1]
	v_pk_add_f32 v[102:103], v[102:103], v[66:67] neg_lo:[0,1] neg_hi:[0,1]
	v_pk_add_f32 v[66:67], v[64:65], v[80:81] op_sel:[0,1] op_sel_hi:[1,0] neg_hi:[0,1]
	v_pk_add_f32 v[68:69], v[70:71], v[84:85] op_sel:[0,1] op_sel_hi:[1,0] neg_hi:[0,1]
	v_pk_add_f32 v[98:99], v[72:73], v[88:89] op_sel:[0,1] op_sel_hi:[1,0] neg_hi:[0,1]
	v_pk_add_f32 v[76:77], v[78:79], v[92:93] op_sel:[0,1] op_sel_hi:[1,0] neg_hi:[0,1]
	v_pk_add_f32 v[80:81], v[64:65], v[80:81] op_sel:[0,1] op_sel_hi:[1,0] neg_lo:[0,1]
	v_pk_add_f32 v[70:71], v[70:71], v[84:85] op_sel:[0,1] op_sel_hi:[1,0] neg_lo:[0,1]
	v_pk_add_f32 v[88:89], v[72:73], v[88:89] op_sel:[0,1] op_sel_hi:[1,0] neg_lo:[0,1]
	v_pk_add_f32 v[78:79], v[78:79], v[92:93] op_sel:[0,1] op_sel_hi:[1,0] neg_lo:[0,1]
	v_pk_mul_f32 v[92:93], v[68:69], s[70:71] op_sel_hi:[1,0]
	v_pk_mul_f32 v[72:73], v[74:75], s[72:73] op_sel_hi:[1,0]
	v_pk_mul_f32 v[84:85], v[70:71], s[64:65] op_sel_hi:[1,0]
	v_pk_mul_f32 v[64:65], v[98:99], s[72:73] op_sel_hi:[1,0]
	v_pk_mul_f32 v[104:105], v[88:89], s[72:73] op_sel_hi:[1,0]
	v_pk_mul_f32 v[106:107], v[76:77], s[64:65] op_sel_hi:[1,0]
	v_pk_mul_f32 v[108:109], v[102:103], s[72:73] op_sel_hi:[1,0]
	v_pk_mul_f32 v[110:111], v[78:79], s[82:83] op_sel_hi:[1,0]
	v_pk_fma_f32 v[92:93], v[68:69], s[44:45], v[92:93] op_sel:[0,0,1] op_sel_hi:[1,0,0] neg_lo:[0,0,1]
	v_pk_fma_f32 v[72:73], v[74:75], s[76:77], v[72:73] op_sel:[0,0,1] op_sel_hi:[1,0,0] neg_lo:[0,0,1]
	v_pk_fma_f32 v[70:71], v[70:71], s[82:83], v[84:85] op_sel:[0,0,1] op_sel_hi:[1,0,0] neg_lo:[0,0,1]
	v_pk_fma_f32 v[64:65], v[98:99], s[76:77], v[64:65] op_sel:[0,0,1] op_sel_hi:[1,0,0] neg_lo:[0,0,1]
	v_pk_fma_f32 v[104:105], v[88:89], s[72:73], v[104:105] op_sel:[0,0,1] op_sel_hi:[1,0,0] neg_lo:[0,0,1]
	v_pk_fma_f32 v[106:107], v[76:77], s[82:83], v[106:107] op_sel:[0,0,1] op_sel_hi:[1,0,0] neg_lo:[0,0,1]
	v_pk_fma_f32 v[102:103], v[102:103], s[72:73], v[108:109] op_sel:[0,0,1] op_sel_hi:[1,0,0] neg_lo:[0,0,1]
	v_pk_fma_f32 v[110:111], v[78:79], s[64:65], v[110:111] op_sel:[0,0,1] op_sel_hi:[1,0,0] neg_lo:[0,0,1]
	v_pk_add_f32 v[78:79], v[94:95], v[86:87]
	v_pk_add_f32 v[108:109], v[66:67], v[64:65]
	v_pk_add_f32 v[76:77], v[96:97], v[100:101] op_sel:[0,1] op_sel_hi:[1,0] neg_hi:[0,1]
	v_pk_add_f32 v[88:89], v[80:81], v[104:105]
	v_pk_add_f32 v[86:87], v[94:95], v[86:87] neg_lo:[0,1] neg_hi:[0,1]
	v_pk_add_f32 v[64:65], v[66:67], v[64:65] neg_lo:[0,1] neg_hi:[0,1]
	v_pk_add_f32 v[100:101], v[96:97], v[100:101] op_sel:[0,1] op_sel_hi:[1,0] neg_lo:[0,1]
	v_pk_add_f32 v[104:105], v[80:81], v[104:105] neg_lo:[0,1] neg_hi:[0,1]
	v_pk_add_f32 v[80:81], v[90:91], v[82:83]
	v_pk_add_f32 v[96:97], v[92:93], v[106:107]
	v_pk_add_f32 v[66:67], v[72:73], v[102:103]
	v_pk_add_f32 v[94:95], v[70:71], v[110:111]
	v_pk_add_f32 v[82:83], v[90:91], v[82:83] neg_lo:[0,1] neg_hi:[0,1]
	v_pk_add_f32 v[92:93], v[92:93], v[106:107] neg_lo:[0,1] neg_hi:[0,1]
	v_pk_add_f32 v[102:103], v[72:73], v[102:103] neg_lo:[0,1] neg_hi:[0,1]
	v_pk_add_f32 v[70:71], v[70:71], v[110:111] neg_lo:[0,1] neg_hi:[0,1]
	v_pk_add_f32 v[110:111], v[78:79], v[80:81]
	v_pk_add_f32 v[72:73], v[108:109], v[96:97]
	v_pk_add_f32 v[106:107], v[76:77], v[66:67]
	v_pk_add_f32 v[90:91], v[88:89], v[94:95]
	v_pk_add_f32 v[80:81], v[78:79], v[80:81] neg_lo:[0,1] neg_hi:[0,1]
	v_pk_add_f32 v[96:97], v[108:109], v[96:97] neg_lo:[0,1] neg_hi:[0,1]
; #define LAS __attribute__((address_space(3)))
; __device__ __forceinline__ f32x2 cmul(f32x2 a, f32x2 b) { return (f32x2){a.x * b.x - a.y * b.y, a.x * b.y + a.y * b.x}; }
; #define LT() ({ int lt_ = tid; asm volatile("" : "+v"(lt_)); lt_; })
; template <bool INV> __device__ __forceinline__ void bfly16_tab(f32x2 (&x)[16], const LAS f32x2* T, int tstride, int j) {
;     if (INV) {
; #pragma unroll
;         for (int q = 1; q < 16; ++q) { f32x2 p = T[q * tstride + j]; p.y = -p.y; x[q] = cmul(x[q], p); } }
;     dft16<INV>(x);
;     if (!INV) {
; #pragma unroll
;         for (int r = 1; r < 16; ++r) { const f32x2 p = T[r * tstride + j]; x[4 * (r & 3) + (r >> 2)] = cmul(x[4 * (r & 3) + (r >> 2)], p); } }
; }
; __device__ __forceinline__ void hyena_latent(Frame& F, int l, int ch, LAS f32x2* X, const LAS f32x2* TH, const LAS f32x2* TL, GAS f32x2* KS, const LAS float* CT  , bool wr = true) {
;     ...
; #pragma unroll
;             for (int i = 0; i < 8; ++i) { const int b = LT() + NTHR * i; const LAS f32x4* P = (const LAS f32x4*)(X + 4 * b + ((b >> 4) << 2)); const f32x4 u = P[0], v = P[1];
;                 f32x2 x0 = {u.x, u.y}, x1 = {u.z, u.w}, x2 = {v.x, v.y}, x3 = {v.z, v.w}; r4<false>(x0, x1, x2, x3);
;                 kreg[2 * i] = (f32x4){x0.x, x0.y, x1.x, x1.y}; kreg[2 * i + 1] = (f32x4){x2.x, x2.y, x3.x, x3.y}; }
	v_pk_add_f32 v[76:77], v[76:77], v[66:67] neg_lo:[0,1] neg_hi:[0,1]
	v_pk_add_f32 v[94:95], v[88:89], v[94:95] neg_lo:[0,1] neg_hi:[0,1]
	v_pk_add_f32 v[88:89], v[86:87], v[82:83] op_sel:[0,1] op_sel_hi:[1,0] neg_hi:[0,1]
	v_pk_add_f32 v[66:67], v[64:65], v[92:93] op_sel:[0,1] op_sel_hi:[1,0] neg_hi:[0,1]
	v_pk_add_f32 v[108:109], v[100:101], v[102:103] op_sel:[0,1] op_sel_hi:[1,0] neg_hi:[0,1]
	v_pk_add_f32 v[78:79], v[104:105], v[70:71] op_sel:[0,1] op_sel_hi:[1,0] neg_hi:[0,1]
	v_pk_add_f32 v[82:83], v[86:87], v[82:83] op_sel:[0,1] op_sel_hi:[1,0] neg_lo:[0,1]
	v_pk_add_f32 v[92:93], v[64:65], v[92:93] op_sel:[0,1] op_sel_hi:[1,0] neg_lo:[0,1]
	v_pk_add_f32 v[100:101], v[100:101], v[102:103] op_sel:[0,1] op_sel_hi:[1,0] neg_lo:[0,1]
	v_pk_add_f32 v[70:71], v[104:105], v[70:71] op_sel:[0,1] op_sel_hi:[1,0] neg_lo:[0,1]
	v_pk_mul_f32 v[104:105], v[72:73], v[232:233] op_sel:[0,1] op_sel_hi:[1,1]
	v_pk_mul_f32 v[102:103], v[106:107], v[234:235] op_sel:[0,1] op_sel_hi:[1,1]
	v_pk_fma_f32 v[72:73], v[72:73], v[232:233], v[104:105] op_sel:[0,0,1] op_sel_hi:[1,0,0] neg_lo:[0,0,1]
	v_pk_mul_f32 v[104:105], v[90:91], v[208:209] op_sel:[0,1] op_sel_hi:[1,1]
	v_pk_fma_f32 v[102:103], v[106:107], v[234:235], v[102:103] op_sel:[0,0,1] op_sel_hi:[1,0,0] neg_lo:[0,0,1]
	v_pk_mul_f32 v[106:107], v[88:89], v[210:211] op_sel:[0,1] op_sel_hi:[1,1]
	v_pk_fma_f32 v[90:91], v[90:91], v[208:209], v[104:105] op_sel:[0,0,1] op_sel_hi:[1,0,0] neg_lo:[0,0,1]
	v_pk_mul_f32 v[104:105], v[66:67], v[204:205] op_sel:[0,1] op_sel_hi:[1,1]
	v_pk_fma_f32 v[88:89], v[88:89], v[210:211], v[106:107] op_sel:[0,0,1] op_sel_hi:[1,0,0] neg_lo:[0,0,1]
	v_pk_mul_f32 v[106:107], v[108:109], v[206:207] op_sel:[0,1] op_sel_hi:[1,1]
	v_pk_fma_f32 v[104:105], v[66:67], v[204:205], v[104:105] op_sel:[0,0,1] op_sel_hi:[1,0,0] neg_lo:[0,0,1]
	v_pk_mul_f32 v[66:67], v[78:79], v[200:201] op_sel:[0,1] op_sel_hi:[1,1]
	v_pk_fma_f32 v[106:107], v[108:109], v[206:207], v[106:107] op_sel:[0,0,1] op_sel_hi:[1,0,0] neg_lo:[0,0,1]
	v_pk_mul_f32 v[108:109], v[80:81], v[202:203] op_sel:[0,1] op_sel_hi:[1,1]
	v_pk_fma_f32 v[66:67], v[78:79], v[200:201], v[66:67] op_sel:[0,0,1] op_sel_hi:[1,0,0] neg_lo:[0,0,1]
	v_pk_mul_f32 v[78:79], v[96:97], v[196:197] op_sel:[0,1] op_sel_hi:[1,1]
	v_pk_fma_f32 v[108:109], v[80:81], v[202:203], v[108:109] op_sel:[0,0,1] op_sel_hi:[1,0,0] neg_lo:[0,0,1]
	v_pk_mul_f32 v[80:81], v[76:77], v[198:199] op_sel:[0,1] op_sel_hi:[1,1]
	v_pk_fma_f32 v[96:97], v[96:97], v[196:197], v[78:79] op_sel:[0,0,1] op_sel_hi:[1,0,0] neg_lo:[0,0,1]
	v_pk_mul_f32 v[78:79], v[94:95], v[192:193] op_sel:[0,1] op_sel_hi:[1,1]
	v_pk_fma_f32 v[80:81], v[76:77], v[198:199], v[80:81] op_sel:[0,0,1] op_sel_hi:[1,0,0] neg_lo:[0,0,1]
	v_pk_mul_f32 v[76:77], v[82:83], v[194:195] op_sel:[0,1] op_sel_hi:[1,1]
	v_pk_fma_f32 v[78:79], v[94:95], v[192:193], v[78:79] op_sel:[0,0,1] op_sel_hi:[1,0,0] neg_lo:[0,0,1]
	v_pk_mul_f32 v[94:95], v[92:93], v[188:189] op_sel:[0,1] op_sel_hi:[1,1]
	v_pk_fma_f32 v[82:83], v[82:83], v[194:195], v[76:77] op_sel:[0,0,1] op_sel_hi:[1,0,0] neg_lo:[0,0,1]
	v_pk_mul_f32 v[76:77], v[100:101], v[190:191] op_sel:[0,1] op_sel_hi:[1,1]
	v_pk_fma_f32 v[92:93], v[92:93], v[188:189], v[94:95] op_sel:[0,0,1] op_sel_hi:[1,0,0] neg_lo:[0,0,1]
	v_pk_mul_f32 v[94:95], v[70:71], v[186:187] op_sel:[0,1] op_sel_hi:[1,1]
	v_pk_fma_f32 v[100:101], v[100:101], v[190:191], v[76:77] op_sel:[0,0,1] op_sel_hi:[1,0,0] neg_lo:[0,0,1]
	v_pk_fma_f32 v[94:95], v[70:71], v[186:187], v[94:95] op_sel:[0,0,1] op_sel_hi:[1,0,0] neg_lo:[0,0,1]
	ds_write_b64 v151, v[110:111] offset:0
	ds_write_b64 v151, v[72:73] offset:32
	ds_write_b64 v151, v[102:103] offset:64
	ds_write_b64 v151, v[90:91] offset:96
	ds_write_b64 v151, v[88:89] offset:128
	ds_write_b64 v151, v[104:105] offset:160
	ds_write_b64 v151, v[106:107] offset:192
	ds_write_b64 v151, v[66:67] offset:224
	ds_write_b64 v151, v[108:109] offset:256
	ds_write_b64 v151, v[96:97] offset:288
	ds_write_b64 v151, v[80:81] offset:320
	ds_write_b64 v151, v[78:79] offset:352
	ds_write_b64 v151, v[82:83] offset:384
	ds_write_b64 v151, v[92:93] offset:416
	ds_write_b64 v151, v[100:101] offset:448
	ds_write_b64 v151, v[94:95] offset:480
	s_cbranch_scc1 .LBB0_850
	v_pk_add_f32 v[68:69], v[56:57], v[60:61]
	v_pk_add_f32 v[56:57], v[56:57], v[60:61] neg_lo:[0,1] neg_hi:[0,1]
	v_pk_add_f32 v[60:61], v[58:59], v[62:63]
	v_pk_add_f32 v[58:59], v[58:59], v[62:63] neg_lo:[0,1] neg_hi:[0,1]
	v_pk_add_f32 v[66:67], v[68:69], v[60:61]
	v_xor_b32_e32 v71, 0x80000000, v58
	v_mov_b32_e32 v70, v59
	v_pk_add_f32 v[62:63], v[68:69], v[60:61] neg_lo:[0,1] neg_hi:[0,1]
	v_pk_add_f32 v[68:69], v[48:49], v[52:53]
	v_pk_add_f32 v[48:49], v[48:49], v[52:53] neg_lo:[0,1] neg_hi:[0,1]
	v_pk_add_f32 v[52:53], v[50:51], v[54:55]
	v_pk_add_f32 v[50:51], v[50:51], v[54:55] neg_lo:[0,1] neg_hi:[0,1]
	v_pk_add_f32 v[64:65], v[56:57], v[70:71]
	v_pk_add_f32 v[60:61], v[56:57], v[70:71] neg_lo:[0,1] neg_hi:[0,1]
	v_xor_b32_e32 v71, 0x80000000, v50
	v_mov_b32_e32 v70, v51
	v_pk_add_f32 v[58:59], v[68:69], v[52:53]
	v_pk_add_f32 v[54:55], v[68:69], v[52:53] neg_lo:[0,1] neg_hi:[0,1]
	v_pk_add_f32 v[68:69], v[40:41], v[44:45]
	v_pk_add_f32 v[40:41], v[40:41], v[44:45] neg_lo:[0,1] neg_hi:[0,1]
	v_pk_add_f32 v[44:45], v[42:43], v[46:47]
	v_pk_add_f32 v[42:43], v[42:43], v[46:47] neg_lo:[0,1] neg_hi:[0,1]
	v_pk_add_f32 v[56:57], v[48:49], v[70:71]
	v_pk_add_f32 v[52:53], v[48:49], v[70:71] neg_lo:[0,1] neg_hi:[0,1]
	v_xor_b32_e32 v71, 0x80000000, v42
	v_mov_b32_e32 v70, v43
	v_pk_add_f32 v[50:51], v[68:69], v[44:45]
	v_pk_add_f32 v[46:47], v[68:69], v[44:45] neg_lo:[0,1] neg_hi:[0,1]
; #define LAS __attribute__((address_space(3)))
; __device__ __forceinline__ f32x2 cmul(f32x2 a, f32x2 b) { return (f32x2){a.x * b.x - a.y * b.y, a.x * b.y + a.y * b.x}; }
; #define LT() ({ int lt_ = tid; asm volatile("" : "+v"(lt_)); lt_; })
; __device__ __forceinline__ void hyena_latent(Frame& F, int l, int ch, LAS f32x2* X, const LAS f32x2* TH, const LAS f32x2* TL, GAS f32x2* KS, const LAS float* CT  , bool wr = true) {
;     ...
; #pragma unroll
;             for (int i = 0; i < 8; ++i) { const int b = LT() + NTHR * i; const LAS f32x4* P = (const LAS f32x4*)(X + 4 * b + ((b >> 4) << 2)); const f32x4 u = P[0], v = P[1];
;                 f32x2 x0 = {u.x, u.y}, x1 = {u.z, u.w}, x2 = {v.x, v.y}, x3 = {v.z, v.w}; r4<false>(x0, x1, x2, x3);
;                 kreg[2 * i] = (f32x4){x0.x, x0.y, x1.x, x1.y}; kreg[2 * i + 1] = (f32x4){x2.x, x2.y, x3.x, x3.y}; }
;     ...
;             fft_fwd_head(X, TH, TL, tid);
; #pragma unroll
;             for (int i = 0; i < 8; ++i) { const int b = LT() + NTHR * i; LAS f32x4* P = (LAS f32x4*)(X + 4 * b + ((b >> 4) << 2)); const f32x4 u = P[0], v = P[1], k0 = kreg[2 * i], k1 = kreg[2 * i + 1];
;                 f32x2 x0 = {u.x, u.y}, x1 = {u.z, u.w}, x2 = {v.x, v.y}, x3 = {v.z, v.w}; r4<false>(x0, x1, x2, x3);
;                 x0 = cmul(x0, (f32x2){k0.x, k0.y}); x1 = cmul(x1, (f32x2){k0.z, k0.w}); x2 = cmul(x2, (f32x2){k1.x, k1.y}); x3 = cmul(x3, (f32x2){k1.z, k1.w});
;                 r4<true>(x0, x1, x2, x3);
;                 P[0] = (f32x4){x0.x, x0.y, x1.x, x1.y}; P[1] = (f32x4){x2.x, x2.y, x3.x, x3.y};
;                 if (i & 1) asm volatile("" ::: "memory"); }
	v_pk_add_f32 v[68:69], v[32:33], v[36:37]
	v_pk_add_f32 v[32:33], v[32:33], v[36:37] neg_lo:[0,1] neg_hi:[0,1]
	v_pk_add_f32 v[36:37], v[34:35], v[38:39]
	v_pk_add_f32 v[34:35], v[34:35], v[38:39] neg_lo:[0,1] neg_hi:[0,1]
	v_pk_add_f32 v[48:49], v[40:41], v[70:71]
	v_pk_add_f32 v[44:45], v[40:41], v[70:71] neg_lo:[0,1] neg_hi:[0,1]
	v_xor_b32_e32 v71, 0x80000000, v34
	v_mov_b32_e32 v70, v35
	v_pk_add_f32 v[42:43], v[68:69], v[36:37]
	v_pk_add_f32 v[38:39], v[68:69], v[36:37] neg_lo:[0,1] neg_hi:[0,1]
	v_pk_add_f32 v[68:69], v[24:25], v[28:29]
	v_pk_add_f32 v[24:25], v[24:25], v[28:29] neg_lo:[0,1] neg_hi:[0,1]
	v_pk_add_f32 v[28:29], v[26:27], v[30:31]
	v_pk_add_f32 v[26:27], v[26:27], v[30:31] neg_lo:[0,1] neg_hi:[0,1]
	v_pk_add_f32 v[40:41], v[32:33], v[70:71]
	v_pk_add_f32 v[36:37], v[32:33], v[70:71] neg_lo:[0,1] neg_hi:[0,1]
	v_xor_b32_e32 v71, 0x80000000, v26
	v_mov_b32_e32 v70, v27
	v_pk_add_f32 v[34:35], v[68:69], v[28:29]
	v_pk_add_f32 v[30:31], v[68:69], v[28:29] neg_lo:[0,1] neg_hi:[0,1]
	v_pk_add_f32 v[68:69], v[12:13], v[20:21]
	v_pk_add_f32 v[12:13], v[12:13], v[20:21] neg_lo:[0,1] neg_hi:[0,1]
	v_pk_add_f32 v[20:21], v[14:15], v[22:23]
	v_pk_add_f32 v[14:15], v[14:15], v[22:23] neg_lo:[0,1] neg_hi:[0,1]
	v_pk_add_f32 v[32:33], v[24:25], v[70:71]
	v_pk_add_f32 v[28:29], v[24:25], v[70:71] neg_lo:[0,1] neg_hi:[0,1]
	v_xor_b32_e32 v71, 0x80000000, v14
	v_mov_b32_e32 v70, v15
	v_pk_add_f32 v[14:15], v[6:7], v[18:19]
	v_pk_add_f32 v[6:7], v[6:7], v[18:19] neg_lo:[0,1] neg_hi:[0,1]
	v_pk_add_f32 v[26:27], v[68:69], v[20:21]
	v_pk_add_f32 v[24:25], v[12:13], v[70:71]
	v_pk_add_f32 v[22:23], v[68:69], v[20:21] neg_lo:[0,1] neg_hi:[0,1]
	v_pk_add_f32 v[20:21], v[12:13], v[70:71] neg_lo:[0,1] neg_hi:[0,1]
	v_pk_add_f32 v[12:13], v[4:5], v[16:17]
	v_pk_add_f32 v[4:5], v[4:5], v[16:17] neg_lo:[0,1] neg_hi:[0,1]
	v_xor_b32_e32 v69, 0x80000000, v6
	v_mov_b32_e32 v68, v7
	v_pk_add_f32 v[18:19], v[12:13], v[14:15]
	v_pk_add_f32 v[16:17], v[4:5], v[68:69]
	v_pk_add_f32 v[14:15], v[12:13], v[14:15] neg_lo:[0,1] neg_hi:[0,1]
	v_pk_add_f32 v[12:13], v[4:5], v[68:69] neg_lo:[0,1] neg_hi:[0,1]
	v_pk_add_f32 v[68:69], v[0:1], v[8:9]
	v_pk_add_f32 v[0:1], v[0:1], v[8:9] neg_lo:[0,1] neg_hi:[0,1]
	v_pk_add_f32 v[8:9], v[2:3], v[10:11]
	v_pk_add_f32 v[2:3], v[2:3], v[10:11] neg_lo:[0,1] neg_hi:[0,1]
	v_pk_add_f32 v[6:7], v[68:69], v[8:9]
	v_xor_b32_e32 v11, 0x80000000, v2
	v_mov_b32_e32 v10, v3
	v_pk_add_f32 v[2:3], v[68:69], v[8:9] neg_lo:[0,1] neg_hi:[0,1]
	v_mov_b32_e32 v8, v140
	s_waitcnt lgkmcnt(0)
	s_barrier
	v_pk_add_f32 v[4:5], v[0:1], v[10:11]
	v_lshlrev_b32_e32 v201, 1, v140
	v_lshlrev_b32_e32 v200, 5, v140
	v_pk_add_f32 v[0:1], v[0:1], v[10:11] neg_lo:[0,1] neg_hi:[0,1]
	v_and_b32_e32 v201, 0xffffffe0, v201
	v_add3_u32 v200, 0, v200, v201
	v_add_u32_e32 v201, 0x11000, v200
	ds_read_b128 v[68:71], v200 offset:0
	ds_read_b128 v[72:75], v200 offset:16
	ds_read_b128 v[76:79], v200 offset:17408
	ds_read_b128 v[80:83], v200 offset:17424
	ds_read_b128 v[84:87], v200 offset:34816
	ds_read_b128 v[88:91], v200 offset:34832
	ds_read_b128 v[92:95], v200 offset:52224
	ds_read_b128 v[96:99], v200 offset:52240
	ds_read_b128 v[100:103], v201 offset:0
	ds_read_b128 v[104:107], v201 offset:16
	ds_read_b128 v[108:111], v201 offset:17408
	ds_read_b128 v[112:115], v201 offset:17424
	ds_read_b128 v[116:119], v201 offset:34816
	ds_read_b128 v[120:123], v201 offset:34832
	ds_read_b128 v[124:127], v201 offset:52224
	ds_read_b128 v[178:181], v201 offset:52240
	s_mov_b32 s0, 0
	s_mov_b64 s[12:13], -1
	s_waitcnt lgkmcnt(14)
	v_pk_add_f32 v[190:191], v[68:69], v[72:73]
	v_pk_add_f32 v[192:193], v[70:71], v[74:75]
	v_pk_add_f32 v[68:69], v[68:69], v[72:73] neg_lo:[0,1] neg_hi:[0,1]
	v_pk_add_f32 v[70:71], v[70:71], v[74:75] neg_lo:[0,1] neg_hi:[0,1]
	v_pk_add_f32 v[72:73], v[190:191], v[192:193]
	v_pk_add_f32 v[74:75], v[190:191], v[192:193] neg_lo:[0,1] neg_hi:[0,1]
	v_pk_add_f32 v[190:191], v[68:69], v[70:71] op_sel:[0,1] op_sel_hi:[1,0] neg_hi:[0,1]
	v_pk_add_f32 v[192:193], v[68:69], v[70:71] op_sel:[0,1] op_sel_hi:[1,0] neg_lo:[0,1]
	v_pk_mul_f32 v[194:195], v[72:73], v[66:67] op_sel:[0,1] op_sel_hi:[1,1]
	v_pk_mul_f32 v[196:197], v[190:191], v[64:65] op_sel:[0,1] op_sel_hi:[1,1]
	v_pk_mul_f32 v[198:199], v[74:75], v[62:63] op_sel:[0,1] op_sel_hi:[1,1]
	v_pk_mul_f32 v[68:69], v[192:193], v[60:61] op_sel:[0,1] op_sel_hi:[1,1]
	v_pk_fma_f32 v[72:73], v[72:73], v[66:67], v[194:195] op_sel:[0,0,1] op_sel_hi:[1,0,0] neg_lo:[0,0,1]
	v_pk_fma_f32 v[190:191], v[190:191], v[64:65], v[196:197] op_sel:[0,0,1] op_sel_hi:[1,0,0] neg_lo:[0,0,1]
	v_pk_fma_f32 v[74:75], v[74:75], v[62:63], v[198:199] op_sel:[0,0,1] op_sel_hi:[1,0,0] neg_lo:[0,0,1]
	v_pk_fma_f32 v[192:193], v[192:193], v[60:61], v[68:69] op_sel:[0,0,1] op_sel_hi:[1,0,0] neg_lo:[0,0,1]
	v_pk_add_f32 v[194:195], v[72:73], v[74:75]
	v_pk_add_f32 v[196:197], v[190:191], v[192:193]
	v_pk_add_f32 v[198:199], v[72:73], v[74:75] neg_lo:[0,1] neg_hi:[0,1]
	v_pk_add_f32 v[68:69], v[190:191], v[192:193] neg_lo:[0,1] neg_hi:[0,1]
	v_pk_add_f32 v[182:183], v[194:195], v[196:197]
	v_pk_add_f32 v[186:187], v[194:195], v[196:197] neg_lo:[0,1] neg_hi:[0,1]
	v_pk_add_f32 v[184:185], v[198:199], v[68:69] op_sel:[0,1] op_sel_hi:[1,0] neg_lo:[0,1]
	v_pk_add_f32 v[188:189], v[198:199], v[68:69] op_sel:[0,1] op_sel_hi:[1,0] neg_hi:[0,1]
	s_nop 0
	ds_write_b128 v200, v[182:185] offset:0
	ds_write_b128 v200, v[186:189] offset:16
	s_waitcnt lgkmcnt(14)
; #define LAS __attribute__((address_space(3)))
; __device__ __forceinline__ f32x2 cmul(f32x2 a, f32x2 b) { return (f32x2){a.x * b.x - a.y * b.y, a.x * b.y + a.y * b.x}; }
; #define LT() ({ int lt_ = tid; asm volatile("" : "+v"(lt_)); lt_; })
; __device__ __forceinline__ void hyena_latent(Frame& F, int l, int ch, LAS f32x2* X, const LAS f32x2* TH, const LAS f32x2* TL, GAS f32x2* KS, const LAS float* CT  , bool wr = true) {
;     ...
;             for (int i = 0; i < 8; ++i) { const int b = LT() + NTHR * i; LAS f32x4* P = (LAS f32x4*)(X + 4 * b + ((b >> 4) << 2)); const f32x4 u = P[0], v = P[1], k0 = kreg[2 * i], k1 = kreg[2 * i + 1];
;                 f32x2 x0 = {u.x, u.y}, x1 = {u.z, u.w}, x2 = {v.x, v.y}, x3 = {v.z, v.w}; r4<false>(x0, x1, x2, x3);
;                 x0 = cmul(x0, (f32x2){k0.x, k0.y}); x1 = cmul(x1, (f32x2){k0.z, k0.w}); x2 = cmul(x2, (f32x2){k1.x, k1.y}); x3 = cmul(x3, (f32x2){k1.z, k1.w});
;                 r4<true>(x0, x1, x2, x3);
;                 P[0] = (f32x4){x0.x, x0.y, x1.x, x1.y}; P[1] = (f32x4){x2.x, x2.y, x3.x, x3.y};
;                 if (i & 1) asm volatile("" ::: "memory"); }
	v_pk_add_f32 v[190:191], v[76:77], v[80:81]
	v_pk_add_f32 v[192:193], v[78:79], v[82:83]
	v_pk_add_f32 v[76:77], v[76:77], v[80:81] neg_lo:[0,1] neg_hi:[0,1]
	v_pk_add_f32 v[78:79], v[78:79], v[82:83] neg_lo:[0,1] neg_hi:[0,1]
	v_pk_add_f32 v[80:81], v[190:191], v[192:193]
	v_pk_add_f32 v[82:83], v[190:191], v[192:193] neg_lo:[0,1] neg_hi:[0,1]
	v_pk_add_f32 v[190:191], v[76:77], v[78:79] op_sel:[0,1] op_sel_hi:[1,0] neg_hi:[0,1]
	v_pk_add_f32 v[192:193], v[76:77], v[78:79] op_sel:[0,1] op_sel_hi:[1,0] neg_lo:[0,1]
	v_pk_mul_f32 v[194:195], v[80:81], v[58:59] op_sel:[0,1] op_sel_hi:[1,1]
	v_pk_mul_f32 v[196:197], v[190:191], v[56:57] op_sel:[0,1] op_sel_hi:[1,1]
	v_pk_mul_f32 v[198:199], v[82:83], v[54:55] op_sel:[0,1] op_sel_hi:[1,1]
	v_pk_mul_f32 v[76:77], v[192:193], v[52:53] op_sel:[0,1] op_sel_hi:[1,1]
	v_pk_fma_f32 v[80:81], v[80:81], v[58:59], v[194:195] op_sel:[0,0,1] op_sel_hi:[1,0,0] neg_lo:[0,0,1]
	v_pk_fma_f32 v[190:191], v[190:191], v[56:57], v[196:197] op_sel:[0,0,1] op_sel_hi:[1,0,0] neg_lo:[0,0,1]
	v_pk_fma_f32 v[82:83], v[82:83], v[54:55], v[198:199] op_sel:[0,0,1] op_sel_hi:[1,0,0] neg_lo:[0,0,1]
	v_pk_fma_f32 v[192:193], v[192:193], v[52:53], v[76:77] op_sel:[0,0,1] op_sel_hi:[1,0,0] neg_lo:[0,0,1]
	v_pk_add_f32 v[194:195], v[80:81], v[82:83]
	v_pk_add_f32 v[196:197], v[190:191], v[192:193]
	v_pk_add_f32 v[198:199], v[80:81], v[82:83] neg_lo:[0,1] neg_hi:[0,1]
	v_pk_add_f32 v[76:77], v[190:191], v[192:193] neg_lo:[0,1] neg_hi:[0,1]
	v_pk_add_f32 v[182:183], v[194:195], v[196:197]
	v_pk_add_f32 v[186:187], v[194:195], v[196:197] neg_lo:[0,1] neg_hi:[0,1]
	v_pk_add_f32 v[184:185], v[198:199], v[76:77] op_sel:[0,1] op_sel_hi:[1,0] neg_lo:[0,1]
	v_pk_add_f32 v[188:189], v[198:199], v[76:77] op_sel:[0,1] op_sel_hi:[1,0] neg_hi:[0,1]
	s_nop 0
	ds_write_b128 v200, v[182:185] offset:17408
	ds_write_b128 v200, v[186:189] offset:17424
	s_waitcnt lgkmcnt(14)
	v_pk_add_f32 v[190:191], v[84:85], v[88:89]
	v_pk_add_f32 v[192:193], v[86:87], v[90:91]
	v_pk_add_f32 v[84:85], v[84:85], v[88:89] neg_lo:[0,1] neg_hi:[0,1]
	v_pk_add_f32 v[86:87], v[86:87], v[90:91] neg_lo:[0,1] neg_hi:[0,1]
	v_pk_add_f32 v[88:89], v[190:191], v[192:193]
	v_pk_add_f32 v[90:91], v[190:191], v[192:193] neg_lo:[0,1] neg_hi:[0,1]
	v_pk_add_f32 v[190:191], v[84:85], v[86:87] op_sel:[0,1] op_sel_hi:[1,0] neg_hi:[0,1]
	v_pk_add_f32 v[192:193], v[84:85], v[86:87] op_sel:[0,1] op_sel_hi:[1,0] neg_lo:[0,1]
	v_pk_mul_f32 v[194:195], v[88:89], v[50:51] op_sel:[0,1] op_sel_hi:[1,1]
	v_pk_mul_f32 v[196:197], v[190:191], v[48:49] op_sel:[0,1] op_sel_hi:[1,1]
	v_pk_mul_f32 v[198:199], v[90:91], v[46:47] op_sel:[0,1] op_sel_hi:[1,1]
	v_pk_mul_f32 v[84:85], v[192:193], v[44:45] op_sel:[0,1] op_sel_hi:[1,1]
	v_pk_fma_f32 v[88:89], v[88:89], v[50:51], v[194:195] op_sel:[0,0,1] op_sel_hi:[1,0,0] neg_lo:[0,0,1]
	v_pk_fma_f32 v[190:191], v[190:191], v[48:49], v[196:197] op_sel:[0,0,1] op_sel_hi:[1,0,0] neg_lo:[0,0,1]
	v_pk_fma_f32 v[90:91], v[90:91], v[46:47], v[198:199] op_sel:[0,0,1] op_sel_hi:[1,0,0] neg_lo:[0,0,1]
	v_pk_fma_f32 v[192:193], v[192:193], v[44:45], v[84:85] op_sel:[0,0,1] op_sel_hi:[1,0,0] neg_lo:[0,0,1]
	v_pk_add_f32 v[194:195], v[88:89], v[90:91]
	v_pk_add_f32 v[196:197], v[190:191], v[192:193]
	v_pk_add_f32 v[198:199], v[88:89], v[90:91] neg_lo:[0,1] neg_hi:[0,1]
	v_pk_add_f32 v[84:85], v[190:191], v[192:193] neg_lo:[0,1] neg_hi:[0,1]
	v_pk_add_f32 v[182:183], v[194:195], v[196:197]
	v_pk_add_f32 v[186:187], v[194:195], v[196:197] neg_lo:[0,1] neg_hi:[0,1]
	v_pk_add_f32 v[184:185], v[198:199], v[84:85] op_sel:[0,1] op_sel_hi:[1,0] neg_lo:[0,1]
	v_pk_add_f32 v[188:189], v[198:199], v[84:85] op_sel:[0,1] op_sel_hi:[1,0] neg_hi:[0,1]
	s_nop 0
	ds_write_b128 v200, v[182:185] offset:34816
	ds_write_b128 v200, v[186:189] offset:34832
	s_waitcnt lgkmcnt(14)
	v_pk_add_f32 v[190:191], v[92:93], v[96:97]
	v_pk_add_f32 v[192:193], v[94:95], v[98:99]
	v_pk_add_f32 v[92:93], v[92:93], v[96:97] neg_lo:[0,1] neg_hi:[0,1]
	v_pk_add_f32 v[94:95], v[94:95], v[98:99] neg_lo:[0,1] neg_hi:[0,1]
	v_pk_add_f32 v[96:97], v[190:191], v[192:193]
	v_pk_add_f32 v[98:99], v[190:191], v[192:193] neg_lo:[0,1] neg_hi:[0,1]
	v_pk_add_f32 v[190:191], v[92:93], v[94:95] op_sel:[0,1] op_sel_hi:[1,0] neg_hi:[0,1]
	v_pk_add_f32 v[192:193], v[92:93], v[94:95] op_sel:[0,1] op_sel_hi:[1,0] neg_lo:[0,1]
	v_pk_mul_f32 v[194:195], v[96:97], v[42:43] op_sel:[0,1] op_sel_hi:[1,1]
	v_pk_mul_f32 v[196:197], v[190:191], v[40:41] op_sel:[0,1] op_sel_hi:[1,1]
	v_pk_mul_f32 v[198:199], v[98:99], v[38:39] op_sel:[0,1] op_sel_hi:[1,1]
	v_pk_mul_f32 v[92:93], v[192:193], v[36:37] op_sel:[0,1] op_sel_hi:[1,1]
	v_pk_fma_f32 v[96:97], v[96:97], v[42:43], v[194:195] op_sel:[0,0,1] op_sel_hi:[1,0,0] neg_lo:[0,0,1]
	v_pk_fma_f32 v[190:191], v[190:191], v[40:41], v[196:197] op_sel:[0,0,1] op_sel_hi:[1,0,0] neg_lo:[0,0,1]
	v_pk_fma_f32 v[98:99], v[98:99], v[38:39], v[198:199] op_sel:[0,0,1] op_sel_hi:[1,0,0] neg_lo:[0,0,1]
	v_pk_fma_f32 v[192:193], v[192:193], v[36:37], v[92:93] op_sel:[0,0,1] op_sel_hi:[1,0,0] neg_lo:[0,0,1]
	v_pk_add_f32 v[194:195], v[96:97], v[98:99]
	v_pk_add_f32 v[196:197], v[190:191], v[192:193]
	v_pk_add_f32 v[198:199], v[96:97], v[98:99] neg_lo:[0,1] neg_hi:[0,1]
	v_pk_add_f32 v[92:93], v[190:191], v[192:193] neg_lo:[0,1] neg_hi:[0,1]
	v_pk_add_f32 v[182:183], v[194:195], v[196:197]
	v_pk_add_f32 v[186:187], v[194:195], v[196:197] neg_lo:[0,1] neg_hi:[0,1]
	v_pk_add_f32 v[184:185], v[198:199], v[92:93] op_sel:[0,1] op_sel_hi:[1,0] neg_lo:[0,1]
	v_pk_add_f32 v[188:189], v[198:199], v[92:93] op_sel:[0,1] op_sel_hi:[1,0] neg_hi:[0,1]
	s_nop 0
	ds_write_b128 v200, v[182:185] offset:52224
	ds_write_b128 v200, v[186:189] offset:52240
	s_waitcnt lgkmcnt(14)
; #define LAS __attribute__((address_space(3)))
; __device__ __forceinline__ f32x2 cmul(f32x2 a, f32x2 b) { return (f32x2){a.x * b.x - a.y * b.y, a.x * b.y + a.y * b.x}; }
; #define LT() ({ int lt_ = tid; asm volatile("" : "+v"(lt_)); lt_; })
; __device__ __forceinline__ void hyena_latent(Frame& F, int l, int ch, LAS f32x2* X, const LAS f32x2* TH, const LAS f32x2* TL, GAS f32x2* KS, const LAS float* CT  , bool wr = true) {
;     ...
;             for (int i = 0; i < 8; ++i) { const int b = LT() + NTHR * i; LAS f32x4* P = (LAS f32x4*)(X + 4 * b + ((b >> 4) << 2)); const f32x4 u = P[0], v = P[1], k0 = kreg[2 * i], k1 = kreg[2 * i + 1];
;                 f32x2 x0 = {u.x, u.y}, x1 = {u.z, u.w}, x2 = {v.x, v.y}, x3 = {v.z, v.w}; r4<false>(x0, x1, x2, x3);
;                 x0 = cmul(x0, (f32x2){k0.x, k0.y}); x1 = cmul(x1, (f32x2){k0.z, k0.w}); x2 = cmul(x2, (f32x2){k1.x, k1.y}); x3 = cmul(x3, (f32x2){k1.z, k1.w});
;                 r4<true>(x0, x1, x2, x3);
;                 P[0] = (f32x4){x0.x, x0.y, x1.x, x1.y}; P[1] = (f32x4){x2.x, x2.y, x3.x, x3.y};
;                 if (i & 1) asm volatile("" ::: "memory"); }
	v_pk_add_f32 v[190:191], v[100:101], v[104:105]
	v_pk_add_f32 v[192:193], v[102:103], v[106:107]
	v_pk_add_f32 v[100:101], v[100:101], v[104:105] neg_lo:[0,1] neg_hi:[0,1]
	v_pk_add_f32 v[102:103], v[102:103], v[106:107] neg_lo:[0,1] neg_hi:[0,1]
	v_pk_add_f32 v[104:105], v[190:191], v[192:193]
	v_pk_add_f32 v[106:107], v[190:191], v[192:193] neg_lo:[0,1] neg_hi:[0,1]
	v_pk_add_f32 v[190:191], v[100:101], v[102:103] op_sel:[0,1] op_sel_hi:[1,0] neg_hi:[0,1]
	v_pk_add_f32 v[192:193], v[100:101], v[102:103] op_sel:[0,1] op_sel_hi:[1,0] neg_lo:[0,1]
	v_pk_mul_f32 v[194:195], v[104:105], v[34:35] op_sel:[0,1] op_sel_hi:[1,1]
	v_pk_mul_f32 v[196:197], v[190:191], v[32:33] op_sel:[0,1] op_sel_hi:[1,1]
	v_pk_mul_f32 v[198:199], v[106:107], v[30:31] op_sel:[0,1] op_sel_hi:[1,1]
	v_pk_mul_f32 v[100:101], v[192:193], v[28:29] op_sel:[0,1] op_sel_hi:[1,1]
	v_pk_fma_f32 v[104:105], v[104:105], v[34:35], v[194:195] op_sel:[0,0,1] op_sel_hi:[1,0,0] neg_lo:[0,0,1]
	v_pk_fma_f32 v[190:191], v[190:191], v[32:33], v[196:197] op_sel:[0,0,1] op_sel_hi:[1,0,0] neg_lo:[0,0,1]
	v_pk_fma_f32 v[106:107], v[106:107], v[30:31], v[198:199] op_sel:[0,0,1] op_sel_hi:[1,0,0] neg_lo:[0,0,1]
	v_pk_fma_f32 v[192:193], v[192:193], v[28:29], v[100:101] op_sel:[0,0,1] op_sel_hi:[1,0,0] neg_lo:[0,0,1]
	v_pk_add_f32 v[194:195], v[104:105], v[106:107]
	v_pk_add_f32 v[196:197], v[190:191], v[192:193]
	v_pk_add_f32 v[198:199], v[104:105], v[106:107] neg_lo:[0,1] neg_hi:[0,1]
	v_pk_add_f32 v[100:101], v[190:191], v[192:193] neg_lo:[0,1] neg_hi:[0,1]
	v_pk_add_f32 v[182:183], v[194:195], v[196:197]
	v_pk_add_f32 v[186:187], v[194:195], v[196:197] neg_lo:[0,1] neg_hi:[0,1]
	v_pk_add_f32 v[184:185], v[198:199], v[100:101] op_sel:[0,1] op_sel_hi:[1,0] neg_lo:[0,1]
	v_pk_add_f32 v[188:189], v[198:199], v[100:101] op_sel:[0,1] op_sel_hi:[1,0] neg_hi:[0,1]
	s_nop 0
	ds_write_b128 v201, v[182:185] offset:0
	ds_write_b128 v201, v[186:189] offset:16
	s_waitcnt lgkmcnt(14)
	v_pk_add_f32 v[190:191], v[108:109], v[112:113]
	v_pk_add_f32 v[192:193], v[110:111], v[114:115]
	v_pk_add_f32 v[108:109], v[108:109], v[112:113] neg_lo:[0,1] neg_hi:[0,1]
	v_pk_add_f32 v[110:111], v[110:111], v[114:115] neg_lo:[0,1] neg_hi:[0,1]
	v_pk_add_f32 v[112:113], v[190:191], v[192:193]
	v_pk_add_f32 v[114:115], v[190:191], v[192:193] neg_lo:[0,1] neg_hi:[0,1]
	v_pk_add_f32 v[190:191], v[108:109], v[110:111] op_sel:[0,1] op_sel_hi:[1,0] neg_hi:[0,1]
	v_pk_add_f32 v[192:193], v[108:109], v[110:111] op_sel:[0,1] op_sel_hi:[1,0] neg_lo:[0,1]
	v_pk_mul_f32 v[194:195], v[112:113], v[26:27] op_sel:[0,1] op_sel_hi:[1,1]
	v_pk_mul_f32 v[196:197], v[190:191], v[24:25] op_sel:[0,1] op_sel_hi:[1,1]
	v_pk_mul_f32 v[198:199], v[114:115], v[22:23] op_sel:[0,1] op_sel_hi:[1,1]
	v_pk_mul_f32 v[108:109], v[192:193], v[20:21] op_sel:[0,1] op_sel_hi:[1,1]
	v_pk_fma_f32 v[112:113], v[112:113], v[26:27], v[194:195] op_sel:[0,0,1] op_sel_hi:[1,0,0] neg_lo:[0,0,1]
	v_pk_fma_f32 v[190:191], v[190:191], v[24:25], v[196:197] op_sel:[0,0,1] op_sel_hi:[1,0,0] neg_lo:[0,0,1]
	v_pk_fma_f32 v[114:115], v[114:115], v[22:23], v[198:199] op_sel:[0,0,1] op_sel_hi:[1,0,0] neg_lo:[0,0,1]
	v_pk_fma_f32 v[192:193], v[192:193], v[20:21], v[108:109] op_sel:[0,0,1] op_sel_hi:[1,0,0] neg_lo:[0,0,1]
	v_pk_add_f32 v[194:195], v[112:113], v[114:115]
	v_pk_add_f32 v[196:197], v[190:191], v[192:193]
	v_pk_add_f32 v[198:199], v[112:113], v[114:115] neg_lo:[0,1] neg_hi:[0,1]
	v_pk_add_f32 v[108:109], v[190:191], v[192:193] neg_lo:[0,1] neg_hi:[0,1]
	v_pk_add_f32 v[182:183], v[194:195], v[196:197]
	v_pk_add_f32 v[186:187], v[194:195], v[196:197] neg_lo:[0,1] neg_hi:[0,1]
	v_pk_add_f32 v[184:185], v[198:199], v[108:109] op_sel:[0,1] op_sel_hi:[1,0] neg_lo:[0,1]
	v_pk_add_f32 v[188:189], v[198:199], v[108:109] op_sel:[0,1] op_sel_hi:[1,0] neg_hi:[0,1]
	s_nop 0
	ds_write_b128 v201, v[182:185] offset:17408
	ds_write_b128 v201, v[186:189] offset:17424
	s_waitcnt lgkmcnt(14)
; #define LAS __attribute__((address_space(3)))
; __device__ __forceinline__ f32x2 cmul(f32x2 a, f32x2 b) { return (f32x2){a.x * b.x - a.y * b.y, a.x * b.y + a.y * b.x}; }
; #define LT() ({ int lt_ = tid; asm volatile("" : "+v"(lt_)); lt_; })
; __device__ __forceinline__ void hyena_latent(Frame& F, int l, int ch, LAS f32x2* X, const LAS f32x2* TH, const LAS f32x2* TL, GAS f32x2* KS, const LAS float* CT  , bool wr = true) {
;     ...
;             for (int i = 0; i < 8; ++i) { const int b = LT() + NTHR * i; LAS f32x4* P = (LAS f32x4*)(X + 4 * b + ((b >> 4) << 2)); const f32x4 u = P[0], v = P[1], k0 = kreg[2 * i], k1 = kreg[2 * i + 1];
;                 f32x2 x0 = {u.x, u.y}, x1 = {u.z, u.w}, x2 = {v.x, v.y}, x3 = {v.z, v.w}; r4<false>(x0, x1, x2, x3);
;                 x0 = cmul(x0, (f32x2){k0.x, k0.y}); x1 = cmul(x1, (f32x2){k0.z, k0.w}); x2 = cmul(x2, (f32x2){k1.x, k1.y}); x3 = cmul(x3, (f32x2){k1.z, k1.w});
;                 r4<true>(x0, x1, x2, x3);
;                 P[0] = (f32x4){x0.x, x0.y, x1.x, x1.y}; P[1] = (f32x4){x2.x, x2.y, x3.x, x3.y};
;                 if (i & 1) asm volatile("" ::: "memory"); }
;             __syncthreads();
;             fft_inv_tail(X, TH, TL, tid);
	v_pk_add_f32 v[190:191], v[116:117], v[120:121]
	v_pk_add_f32 v[192:193], v[118:119], v[122:123]
	v_pk_add_f32 v[116:117], v[116:117], v[120:121] neg_lo:[0,1] neg_hi:[0,1]
	v_pk_add_f32 v[118:119], v[118:119], v[122:123] neg_lo:[0,1] neg_hi:[0,1]
	v_pk_add_f32 v[120:121], v[190:191], v[192:193]
	v_pk_add_f32 v[122:123], v[190:191], v[192:193] neg_lo:[0,1] neg_hi:[0,1]
	v_pk_add_f32 v[190:191], v[116:117], v[118:119] op_sel:[0,1] op_sel_hi:[1,0] neg_hi:[0,1]
	v_pk_add_f32 v[192:193], v[116:117], v[118:119] op_sel:[0,1] op_sel_hi:[1,0] neg_lo:[0,1]
	v_pk_mul_f32 v[194:195], v[120:121], v[18:19] op_sel:[0,1] op_sel_hi:[1,1]
	v_pk_mul_f32 v[196:197], v[190:191], v[16:17] op_sel:[0,1] op_sel_hi:[1,1]
	v_pk_mul_f32 v[198:199], v[122:123], v[14:15] op_sel:[0,1] op_sel_hi:[1,1]
	v_pk_mul_f32 v[116:117], v[192:193], v[12:13] op_sel:[0,1] op_sel_hi:[1,1]
	v_pk_fma_f32 v[120:121], v[120:121], v[18:19], v[194:195] op_sel:[0,0,1] op_sel_hi:[1,0,0] neg_lo:[0,0,1]
	v_pk_fma_f32 v[190:191], v[190:191], v[16:17], v[196:197] op_sel:[0,0,1] op_sel_hi:[1,0,0] neg_lo:[0,0,1]
	v_pk_fma_f32 v[122:123], v[122:123], v[14:15], v[198:199] op_sel:[0,0,1] op_sel_hi:[1,0,0] neg_lo:[0,0,1]
	v_pk_fma_f32 v[192:193], v[192:193], v[12:13], v[116:117] op_sel:[0,0,1] op_sel_hi:[1,0,0] neg_lo:[0,0,1]
	v_pk_add_f32 v[194:195], v[120:121], v[122:123]
	v_pk_add_f32 v[196:197], v[190:191], v[192:193]
	v_pk_add_f32 v[198:199], v[120:121], v[122:123] neg_lo:[0,1] neg_hi:[0,1]
	v_pk_add_f32 v[116:117], v[190:191], v[192:193] neg_lo:[0,1] neg_hi:[0,1]
	v_pk_add_f32 v[182:183], v[194:195], v[196:197]
	v_pk_add_f32 v[186:187], v[194:195], v[196:197] neg_lo:[0,1] neg_hi:[0,1]
	v_pk_add_f32 v[184:185], v[198:199], v[116:117] op_sel:[0,1] op_sel_hi:[1,0] neg_lo:[0,1]
	v_pk_add_f32 v[188:189], v[198:199], v[116:117] op_sel:[0,1] op_sel_hi:[1,0] neg_hi:[0,1]
	s_nop 0
	ds_write_b128 v201, v[182:185] offset:34816
	ds_write_b128 v201, v[186:189] offset:34832
	s_waitcnt lgkmcnt(14)
	v_pk_add_f32 v[190:191], v[124:125], v[178:179]
	v_pk_add_f32 v[192:193], v[126:127], v[180:181]
	v_pk_add_f32 v[124:125], v[124:125], v[178:179] neg_lo:[0,1] neg_hi:[0,1]
	v_pk_add_f32 v[126:127], v[126:127], v[180:181] neg_lo:[0,1] neg_hi:[0,1]
	v_pk_add_f32 v[178:179], v[190:191], v[192:193]
	v_pk_add_f32 v[180:181], v[190:191], v[192:193] neg_lo:[0,1] neg_hi:[0,1]
	v_pk_add_f32 v[190:191], v[124:125], v[126:127] op_sel:[0,1] op_sel_hi:[1,0] neg_hi:[0,1]
	v_pk_add_f32 v[192:193], v[124:125], v[126:127] op_sel:[0,1] op_sel_hi:[1,0] neg_lo:[0,1]
	v_pk_mul_f32 v[194:195], v[178:179], v[6:7] op_sel:[0,1] op_sel_hi:[1,1]
	v_pk_mul_f32 v[196:197], v[190:191], v[4:5] op_sel:[0,1] op_sel_hi:[1,1]
	v_pk_mul_f32 v[198:199], v[180:181], v[2:3] op_sel:[0,1] op_sel_hi:[1,1]
	v_pk_mul_f32 v[124:125], v[192:193], v[0:1] op_sel:[0,1] op_sel_hi:[1,1]
	v_pk_fma_f32 v[178:179], v[178:179], v[6:7], v[194:195] op_sel:[0,0,1] op_sel_hi:[1,0,0] neg_lo:[0,0,1]
	v_pk_fma_f32 v[190:191], v[190:191], v[4:5], v[196:197] op_sel:[0,0,1] op_sel_hi:[1,0,0] neg_lo:[0,0,1]
	v_pk_fma_f32 v[180:181], v[180:181], v[2:3], v[198:199] op_sel:[0,0,1] op_sel_hi:[1,0,0] neg_lo:[0,0,1]
	v_pk_fma_f32 v[192:193], v[192:193], v[0:1], v[124:125] op_sel:[0,0,1] op_sel_hi:[1,0,0] neg_lo:[0,0,1]
	v_pk_add_f32 v[194:195], v[178:179], v[180:181]
	v_pk_add_f32 v[196:197], v[190:191], v[192:193]
	v_pk_add_f32 v[198:199], v[178:179], v[180:181] neg_lo:[0,1] neg_hi:[0,1]
	v_pk_add_f32 v[124:125], v[190:191], v[192:193] neg_lo:[0,1] neg_hi:[0,1]
	v_pk_add_f32 v[182:183], v[194:195], v[196:197]
	v_pk_add_f32 v[186:187], v[194:195], v[196:197] neg_lo:[0,1] neg_hi:[0,1]
	v_pk_add_f32 v[184:185], v[198:199], v[124:125] op_sel:[0,1] op_sel_hi:[1,0] neg_lo:[0,1]
	v_pk_add_f32 v[188:189], v[198:199], v[124:125] op_sel:[0,1] op_sel_hi:[1,0] neg_hi:[0,1]
	s_nop 0
	ds_write_b128 v201, v[182:185] offset:52224
	ds_write_b128 v201, v[186:189] offset:52240
	s_waitcnt lgkmcnt(0)
	s_barrier
	ds_read2_b64 v[232:235], v141 offset0:4 offset1:8
	ds_read2_b64 v[208:211], v141 offset0:12 offset1:16
	ds_read2_b64 v[204:207], v141 offset0:20 offset1:24
	ds_read2_b64 v[200:203], v141 offset0:28 offset1:32
	ds_read2_b64 v[196:199], v141 offset0:36 offset1:40
	ds_read2_b64 v[192:195], v141 offset0:44 offset1:48
	ds_read2_b64 v[188:191], v141 offset0:52 offset1:56
	ds_read_b64 v[186:187], v141 offset:480

; #define LAS __attribute__((address_space(3)))
; __device__ __forceinline__ f32x2 cmul(f32x2 a, f32x2 b) { return (f32x2){a.x * b.x - a.y * b.y, a.x * b.y + a.y * b.x}; }
; __device__ __forceinline__ f32x2 tw32k(const LAS f32x2* TH, const LAS f32x2* TL, int n) { return cmul(TH[n >> 7], TL[n & 127]); }
; template <bool INV> __device__ __forceinline__ void bfly16(f32x2 (&x)[16], const LAS f32x2* TH, const LAS f32x2* TL, int tw) {
;     f32x2 W = tw32k(TH, TL, tw); if (INV) W.y = -W.y;
;     if (INV) { f32x2 p = W;
; #pragma unroll
;         for (int q = 1; q < 16; ++q) { x[q] = cmul(x[q], p); if (q < 15) p = cmul(p, W); } }
;     dft16<INV>(x);
;     if (!INV) { f32x2 p = W;
; #pragma unroll
;         for (int r = 1; r < 16; ++r) { x[4 * (r & 3) + (r >> 2)] = cmul(x[4 * (r & 3) + (r >> 2)], p); if (r < 15) p = cmul(p, W); } }
; }
; template <bool INV> __device__ __forceinline__ void pass16(LAS f32x2* X, const LAS f32x2* TH, const LAS f32x2* TL, int base, int stride, int tw) {
;     f32x2 x[16];
; #pragma unroll
;     for (int q = 0; q < 16; ++q) x[q] = X[base + q * stride];
;     bfly16<INV>(x, TH, TL, tw);
; #pragma unroll
;     for (int c = 0; c < 4; ++c)
; #pragma unroll
;         for (int d = 0; d < 4; ++d) X[base + (c + 4 * d) * stride] = x[4 * c + d];
; }
.LBB0_856:
	v_add_u32_e32 v128, s0, v140
	v_lshrrev_b32_e32 v147, 6, v128
	v_and_b32_e32 v157, 63, v128
	v_lshlrev_b32_e32 v151, 5, v147
	v_lshlrev_b32_e32 v155, 3, v147
	v_lshlrev_b32_e32 v157, 4, v157
	v_lshl_add_u32 v151, v128, 3, v151
	v_add_u32_e32 v155, 0x26000, v155
	v_add_u32_e32 v157, 0x26400, v157
	v_add_u32_e32 v176, 0x11000, v151
	ds_read_b64 v[0:1], v155
	ds_read_b64 v[2:3], v157
	ds_read_b64 v[4:5], v151 offset:8704
	ds_read_b64 v[6:7], v151 offset:17408
	ds_read_b64 v[8:9], v151 offset:26112
	ds_read_b64 v[10:11], v151 offset:34816
	ds_read_b64 v[12:13], v151 offset:43520
	ds_read_b64 v[14:15], v151 offset:52224
	ds_read_b64 v[16:17], v151 offset:60928
	ds_read_b64 v[18:19], v176 offset:0
	ds_read_b64 v[20:21], v176 offset:8704
	ds_read_b64 v[22:23], v176 offset:17408
	ds_read_b64 v[24:25], v176 offset:26112
	ds_read_b64 v[26:27], v176 offset:34816
	ds_read_b64 v[28:29], v176 offset:43520
	ds_read_b64 v[30:31], v176 offset:52224
	ds_read_b64 v[32:33], v176 offset:60928
	ds_read_b64 v[34:35], v151 offset:0
	s_cmp_eq_u32 s0, 0
	s_movk_i32 s0, 0x200
	s_mov_b64 s[12:13], 0
	s_waitcnt lgkmcnt(15)
	v_pk_mul_f32 v[36:37], v[0:1], v[2:3] op_sel:[0,1] op_sel_hi:[1,1]
	s_nop 0
	v_pk_fma_f32 v[36:37], v[0:1], v[2:3], v[36:37] op_sel:[0,0,1] op_sel_hi:[1,0,0] neg_lo:[0,0,1]
	s_nop 0
	v_pk_mul_f32 v[0:1], v[36:37], v[36:37] op_sel:[0,1] op_sel_hi:[1,1]
	s_nop 0
	v_pk_fma_f32 v[0:1], v[36:37], v[36:37], v[0:1] op_sel:[0,0,1] op_sel_hi:[1,0,0] neg_lo:[0,0,1]
	s_nop 0
	v_pk_mul_f32 v[2:3], v[0:1], v[36:37] op_sel:[0,1] op_sel_hi:[1,1]
	v_pk_mul_f32 v[38:39], v[0:1], v[0:1] op_sel:[0,1] op_sel_hi:[1,1]
	v_pk_fma_f32 v[2:3], v[0:1], v[36:37], v[2:3] op_sel:[0,0,1] op_sel_hi:[1,0,0] neg_lo:[0,0,1]
	v_pk_fma_f32 v[38:39], v[0:1], v[0:1], v[38:39] op_sel:[0,0,1] op_sel_hi:[1,0,0] neg_lo:[0,0,1]
	s_nop 0
	v_pk_mul_f32 v[40:41], v[38:39], v[36:37] op_sel:[0,1] op_sel_hi:[1,1]
	v_pk_mul_f32 v[42:43], v[38:39], v[0:1] op_sel:[0,1] op_sel_hi:[1,1]
	v_pk_mul_f32 v[44:45], v[38:39], v[2:3] op_sel:[0,1] op_sel_hi:[1,1]
	v_pk_fma_f32 v[40:41], v[38:39], v[36:37], v[40:41] op_sel:[0,0,1] op_sel_hi:[1,0,0] neg_lo:[0,0,1]
	v_pk_fma_f32 v[42:43], v[38:39], v[0:1], v[42:43] op_sel:[0,0,1] op_sel_hi:[1,0,0] neg_lo:[0,0,1]
	v_pk_fma_f32 v[44:45], v[38:39], v[2:3], v[44:45] op_sel:[0,0,1] op_sel_hi:[1,0,0] neg_lo:[0,0,1]
	v_pk_mul_f32 v[46:47], v[38:39], v[38:39] op_sel:[0,1] op_sel_hi:[1,1]
	s_nop 0
	v_pk_fma_f32 v[46:47], v[38:39], v[38:39], v[46:47] op_sel:[0,0,1] op_sel_hi:[1,0,0] neg_lo:[0,0,1]
	s_nop 0
	v_pk_mul_f32 v[48:49], v[46:47], v[36:37] op_sel:[0,1] op_sel_hi:[1,1]
	v_pk_mul_f32 v[50:51], v[46:47], v[0:1] op_sel:[0,1] op_sel_hi:[1,1]
	v_pk_mul_f32 v[52:53], v[46:47], v[2:3] op_sel:[0,1] op_sel_hi:[1,1]
	v_pk_fma_f32 v[48:49], v[46:47], v[36:37], v[48:49] op_sel:[0,0,1] op_sel_hi:[1,0,0] neg_lo:[0,0,1]
	v_pk_fma_f32 v[50:51], v[46:47], v[0:1], v[50:51] op_sel:[0,0,1] op_sel_hi:[1,0,0] neg_lo:[0,0,1]
	v_pk_fma_f32 v[52:53], v[46:47], v[2:3], v[52:53] op_sel:[0,0,1] op_sel_hi:[1,0,0] neg_lo:[0,0,1]
	v_pk_mul_f32 v[54:55], v[46:47], v[38:39] op_sel:[0,1] op_sel_hi:[1,1]
	v_pk_mul_f32 v[56:57], v[46:47], v[40:41] op_sel:[0,1] op_sel_hi:[1,1]
	v_pk_mul_f32 v[58:59], v[46:47], v[42:43] op_sel:[0,1] op_sel_hi:[1,1]
	v_pk_fma_f32 v[54:55], v[46:47], v[38:39], v[54:55] op_sel:[0,0,1] op_sel_hi:[1,0,0] neg_lo:[0,0,1]
	v_pk_fma_f32 v[56:57], v[46:47], v[40:41], v[56:57] op_sel:[0,0,1] op_sel_hi:[1,0,0] neg_lo:[0,0,1]
	v_pk_fma_f32 v[58:59], v[46:47], v[42:43], v[58:59] op_sel:[0,0,1] op_sel_hi:[1,0,0] neg_lo:[0,0,1]
	v_pk_mul_f32 v[60:61], v[46:47], v[44:45] op_sel:[0,1] op_sel_hi:[1,1]
	s_nop 0
	v_pk_fma_f32 v[60:61], v[46:47], v[44:45], v[60:61] op_sel:[0,0,1] op_sel_hi:[1,0,0] neg_lo:[0,0,1]
	v_pk_mul_f32 v[62:63], v[4:5], v[36:37] op_sel:[0,1] op_sel_hi:[1,1]
	s_waitcnt lgkmcnt(14)
	v_pk_mul_f32 v[64:65], v[6:7], v[0:1] op_sel:[0,1] op_sel_hi:[1,1]
	v_pk_fma_f32 v[4:5], v[4:5], v[36:37], v[62:63] op_sel:[0,0,1] op_sel_hi:[1,0,0] neg_hi:[0,0,1]
	s_waitcnt lgkmcnt(13)
	v_pk_mul_f32 v[62:63], v[8:9], v[2:3] op_sel:[0,1] op_sel_hi:[1,1]
	v_pk_fma_f32 v[64:65], v[6:7], v[0:1], v[64:65] op_sel:[0,0,1] op_sel_hi:[1,0,0] neg_hi:[0,0,1]
	s_waitcnt lgkmcnt(12)
	v_pk_mul_f32 v[6:7], v[10:11], v[38:39] op_sel:[0,1] op_sel_hi:[1,1]
	v_pk_fma_f32 v[62:63], v[8:9], v[2:3], v[62:63] op_sel:[0,0,1] op_sel_hi:[1,0,0] neg_hi:[0,0,1]
	s_waitcnt lgkmcnt(11)
	v_pk_mul_f32 v[2:3], v[12:13], v[40:41] op_sel:[0,1] op_sel_hi:[1,1]
	v_pk_fma_f32 v[38:39], v[10:11], v[38:39], v[6:7] op_sel:[0,0,1] op_sel_hi:[1,0,0] neg_hi:[0,0,1]
	s_waitcnt lgkmcnt(10)
	v_pk_mul_f32 v[10:11], v[14:15], v[42:43] op_sel:[0,1] op_sel_hi:[1,1]
	v_pk_fma_f32 v[2:3], v[12:13], v[40:41], v[2:3] op_sel:[0,0,1] op_sel_hi:[1,0,0] neg_hi:[0,0,1]
	s_waitcnt lgkmcnt(9)
	v_pk_mul_f32 v[12:13], v[16:17], v[44:45] op_sel:[0,1] op_sel_hi:[1,1]
	v_pk_fma_f32 v[42:43], v[14:15], v[42:43], v[10:11] op_sel:[0,0,1] op_sel_hi:[1,0,0] neg_hi:[0,0,1]
	s_waitcnt lgkmcnt(8)
	v_pk_mul_f32 v[10:11], v[18:19], v[46:47] op_sel:[0,1] op_sel_hi:[1,1]
	v_pk_fma_f32 v[12:13], v[16:17], v[44:45], v[12:13] op_sel:[0,0,1] op_sel_hi:[1,0,0] neg_hi:[0,0,1]
	s_waitcnt lgkmcnt(7)
	v_pk_mul_f32 v[16:17], v[20:21], v[48:49] op_sel:[0,1] op_sel_hi:[1,1]
	v_pk_fma_f32 v[10:11], v[18:19], v[46:47], v[10:11] op_sel:[0,0,1] op_sel_hi:[1,0,0] neg_hi:[0,0,1]
	s_waitcnt lgkmcnt(6)
	v_pk_mul_f32 v[18:19], v[22:23], v[50:51] op_sel:[0,1] op_sel_hi:[1,1]
	v_pk_fma_f32 v[48:49], v[20:21], v[48:49], v[16:17] op_sel:[0,0,1] op_sel_hi:[1,0,0] neg_hi:[0,0,1]
	s_waitcnt lgkmcnt(5)
; __device__ __forceinline__ f32x2 cmul(f32x2 a, f32x2 b) { return (f32x2){a.x * b.x - a.y * b.y, a.x * b.y + a.y * b.x}; }
; template <bool INV> __device__ __forceinline__ void dft16(f32x2 (&x)[16]) {
; #pragma unroll
;     for (int b = 0; b < 4; ++b) r4<INV>(x[b], x[4 + b], x[8 + b], x[12 + b]);
;     const float sg = INV ? -1.f : 1.f;
;     const f32x2 W1 = {0.92387953251f, -0.38268343236f * sg}, W2 = {0.70710678118f, -0.70710678118f * sg}, W3 = {0.38268343236f, -0.92387953251f * sg},
;                 W4 = {0.f, -1.f * sg}, W6 = {-0.70710678118f, -0.70710678118f * sg}, W9 = {-0.92387953251f, 0.38268343236f * sg};
;     x[5] = cmul(x[5], W1); x[9] = cmul(x[9], W2); x[13] = cmul(x[13], W3);
;     x[6] = cmul(x[6], W2); x[10] = cmul(x[10], W4); x[14] = cmul(x[14], W6);
;     x[7] = cmul(x[7], W3); x[11] = cmul(x[11], W6); x[15] = cmul(x[15], W9);
; #pragma unroll
;     for (int c = 0; c < 4; ++c) r4<INV>(x[4 * c], x[4 * c + 1], x[4 * c + 2], x[4 * c + 3]);
; }
	v_pk_mul_f32 v[20:21], v[24:25], v[52:53] op_sel:[0,1] op_sel_hi:[1,1]
	v_pk_fma_f32 v[50:51], v[22:23], v[50:51], v[18:19] op_sel:[0,0,1] op_sel_hi:[1,0,0] neg_hi:[0,0,1]
	s_waitcnt lgkmcnt(4)
	v_pk_mul_f32 v[18:19], v[26:27], v[54:55] op_sel:[0,1] op_sel_hi:[1,1]
	v_pk_fma_f32 v[24:25], v[24:25], v[52:53], v[20:21] op_sel:[0,0,1] op_sel_hi:[1,0,0] neg_hi:[0,0,1]
	s_waitcnt lgkmcnt(3)
	v_pk_mul_f32 v[52:53], v[28:29], v[56:57] op_sel:[0,1] op_sel_hi:[1,1]
	v_pk_fma_f32 v[18:19], v[26:27], v[54:55], v[18:19] op_sel:[0,0,1] op_sel_hi:[1,0,0] neg_hi:[0,0,1]
	s_waitcnt lgkmcnt(2)
	v_pk_mul_f32 v[54:55], v[30:31], v[58:59] op_sel:[0,1] op_sel_hi:[1,1]
	v_pk_fma_f32 v[52:53], v[28:29], v[56:57], v[52:53] op_sel:[0,0,1] op_sel_hi:[1,0,0] neg_hi:[0,0,1]
	s_waitcnt lgkmcnt(1)
	v_pk_mul_f32 v[56:57], v[32:33], v[60:61] op_sel:[0,1] op_sel_hi:[1,1]
	v_pk_fma_f32 v[58:59], v[30:31], v[58:59], v[54:55] op_sel:[0,0,1] op_sel_hi:[1,0,0] neg_hi:[0,0,1]
	v_pk_fma_f32 v[32:33], v[32:33], v[60:61], v[56:57] op_sel:[0,0,1] op_sel_hi:[1,0,0] neg_hi:[0,0,1]
	s_waitcnt lgkmcnt(0)
	v_pk_add_f32 v[56:57], v[34:35], v[10:11]
	v_pk_add_f32 v[60:61], v[4:5], v[48:49]
	v_pk_add_f32 v[30:31], v[64:65], v[50:51]
	v_pk_add_f32 v[54:55], v[62:63], v[24:25]
	v_pk_add_f32 v[10:11], v[34:35], v[10:11] neg_lo:[0,1] neg_hi:[0,1]
	v_pk_add_f32 v[4:5], v[4:5], v[48:49] neg_lo:[0,1] neg_hi:[0,1]
	v_pk_add_f32 v[50:51], v[64:65], v[50:51] neg_lo:[0,1] neg_hi:[0,1]
	v_pk_add_f32 v[62:63], v[62:63], v[24:25] neg_lo:[0,1] neg_hi:[0,1]
	v_pk_add_f32 v[24:25], v[38:39], v[18:19]
	v_pk_add_f32 v[64:65], v[2:3], v[52:53]
	v_pk_add_f32 v[48:49], v[42:43], v[58:59]
	v_pk_add_f32 v[34:35], v[12:13], v[32:33]
	v_pk_add_f32 v[38:39], v[38:39], v[18:19] neg_lo:[0,1] neg_hi:[0,1]
	v_pk_add_f32 v[52:53], v[2:3], v[52:53] neg_lo:[0,1] neg_hi:[0,1]
	v_pk_add_f32 v[42:43], v[42:43], v[58:59] neg_lo:[0,1] neg_hi:[0,1]
	v_pk_add_f32 v[32:33], v[12:13], v[32:33] neg_lo:[0,1] neg_hi:[0,1]
	v_pk_add_f32 v[12:13], v[56:57], v[24:25]
	v_pk_add_f32 v[58:59], v[60:61], v[64:65]
	v_pk_add_f32 v[2:3], v[30:31], v[48:49]
	v_pk_add_f32 v[18:19], v[54:55], v[34:35]
	v_pk_add_f32 v[56:57], v[56:57], v[24:25] neg_lo:[0,1] neg_hi:[0,1]
	v_pk_add_f32 v[60:61], v[60:61], v[64:65] neg_lo:[0,1] neg_hi:[0,1]
	v_pk_add_f32 v[30:31], v[30:31], v[48:49] neg_lo:[0,1] neg_hi:[0,1]
	v_pk_add_f32 v[34:35], v[54:55], v[34:35] neg_lo:[0,1] neg_hi:[0,1]
	v_pk_add_f32 v[54:55], v[10:11], v[38:39] op_sel:[0,1] op_sel_hi:[1,0] neg_lo:[0,1]
	v_pk_add_f32 v[48:49], v[4:5], v[52:53] op_sel:[0,1] op_sel_hi:[1,0] neg_lo:[0,1]
	v_pk_add_f32 v[64:65], v[50:51], v[42:43] op_sel:[0,1] op_sel_hi:[1,0] neg_lo:[0,1]
	v_pk_add_f32 v[24:25], v[62:63], v[32:33] op_sel:[0,1] op_sel_hi:[1,0] neg_lo:[0,1]
	v_pk_add_f32 v[10:11], v[10:11], v[38:39] op_sel:[0,1] op_sel_hi:[1,0] neg_hi:[0,1]
	v_pk_add_f32 v[4:5], v[4:5], v[52:53] op_sel:[0,1] op_sel_hi:[1,0] neg_hi:[0,1]
	v_pk_add_f32 v[50:51], v[50:51], v[42:43] op_sel:[0,1] op_sel_hi:[1,0] neg_hi:[0,1]
	v_pk_add_f32 v[32:33], v[62:63], v[32:33] op_sel:[0,1] op_sel_hi:[1,0] neg_hi:[0,1]
	v_pk_mul_f32 v[62:63], v[48:49], s[82:83] op_sel_hi:[1,0]
	v_pk_mul_f32 v[42:43], v[60:61], s[76:77] op_sel_hi:[1,0]
	v_pk_mul_f32 v[52:53], v[4:5], s[44:45] op_sel_hi:[1,0]
	v_pk_mul_f32 v[38:39], v[64:65], s[76:77] op_sel_hi:[1,0]
	v_pk_mul_f32 v[28:29], v[50:51], s[76:77] op_sel_hi:[1,0]
	v_pk_mul_f32 v[26:27], v[24:25], s[44:45] op_sel_hi:[1,0]
	v_pk_mul_f32 v[20:21], v[34:35], s[76:77] op_sel_hi:[1,0]
	v_pk_mul_f32 v[22:23], v[32:33], s[70:71] op_sel_hi:[1,0]
	v_pk_fma_f32 v[62:63], v[48:49], s[44:45], v[62:63] op_sel:[0,0,1] op_sel_hi:[1,0,0] neg_lo:[0,0,1]
	v_pk_fma_f32 v[60:61], v[60:61], s[76:77], v[42:43] op_sel:[0,0,1] op_sel_hi:[1,0,0] neg_lo:[0,0,1]
	v_pk_fma_f32 v[4:5], v[4:5], s[82:83], v[52:53] op_sel:[0,0,1] op_sel_hi:[1,0,0] neg_lo:[0,0,1]
	v_pk_fma_f32 v[38:39], v[64:65], s[76:77], v[38:39] op_sel:[0,0,1] op_sel_hi:[1,0,0] neg_lo:[0,0,1]
	v_pk_fma_f32 v[50:51], v[50:51], s[72:73], v[28:29] op_sel:[0,0,1] op_sel_hi:[1,0,0] neg_lo:[0,0,1]
	v_pk_fma_f32 v[26:27], v[24:25], s[82:83], v[26:27] op_sel:[0,0,1] op_sel_hi:[1,0,0] neg_lo:[0,0,1]
	v_pk_fma_f32 v[20:21], v[34:35], s[72:73], v[20:21] op_sel:[0,0,1] op_sel_hi:[1,0,0] neg_lo:[0,0,1]
	v_pk_fma_f32 v[32:33], v[32:33], s[64:65], v[22:23] op_sel:[0,0,1] op_sel_hi:[1,0,0] neg_lo:[0,0,1]
	v_pk_add_f32 v[22:23], v[12:13], v[2:3]
	v_pk_add_f32 v[34:35], v[54:55], v[38:39]
	v_pk_add_f32 v[24:25], v[56:57], v[30:31] op_sel:[0,1] op_sel_hi:[1,0] neg_lo:[0,1]
	v_pk_add_f32 v[28:29], v[10:11], v[50:51]
	v_pk_add_f32 v[12:13], v[12:13], v[2:3] neg_lo:[0,1] neg_hi:[0,1]
	v_pk_add_f32 v[54:55], v[54:55], v[38:39] neg_lo:[0,1] neg_hi:[0,1]
	v_pk_add_f32 v[56:57], v[56:57], v[30:31] op_sel:[0,1] op_sel_hi:[1,0] neg_hi:[0,1]
	v_pk_add_f32 v[50:51], v[10:11], v[50:51] neg_lo:[0,1] neg_hi:[0,1]
	v_pk_add_f32 v[10:11], v[58:59], v[18:19]
	v_pk_add_f32 v[30:31], v[62:63], v[26:27]
	v_pk_add_f32 v[38:39], v[60:61], v[20:21]
	v_pk_add_f32 v[2:3], v[4:5], v[32:33]
	v_pk_add_f32 v[58:59], v[58:59], v[18:19] neg_lo:[0,1] neg_hi:[0,1]
	v_pk_add_f32 v[62:63], v[62:63], v[26:27] neg_lo:[0,1] neg_hi:[0,1]
	v_pk_add_f32 v[20:21], v[60:61], v[20:21] neg_lo:[0,1] neg_hi:[0,1]
	v_pk_add_f32 v[4:5], v[4:5], v[32:33] neg_lo:[0,1] neg_hi:[0,1]
	v_pk_add_f32 v[32:33], v[22:23], v[10:11]
	v_pk_add_f32 v[60:61], v[34:35], v[30:31]
	v_pk_add_f32 v[26:27], v[24:25], v[38:39]
; #define LAS __attribute__((address_space(3)))
; #define LT() ({ int lt_ = tid; asm volatile("" : "+v"(lt_)); lt_; })
; template <bool INV> __device__ __forceinline__ void pass16(LAS f32x2* X, const LAS f32x2* TH, const LAS f32x2* TL, int base, int stride, int tw) {
;     f32x2 x[16];
; #pragma unroll
;     for (int q = 0; q < 16; ++q) x[q] = X[base + q * stride];
;     bfly16<INV>(x, TH, TL, tw);
; #pragma unroll
;     for (int c = 0; c < 4; ++c)
; #pragma unroll
;         for (int d = 0; d < 4; ++d) X[base + (c + 4 * d) * stride] = x[4 * c + d];
; }
; __device__ __forceinline__ void hyena_latent(Frame& F, int l, int ch, LAS f32x2* X, const LAS f32x2* TH, const LAS f32x2* TL, GAS f32x2* KS, const LAS float* CT  , bool wr = true) {
;     ...
;             if (par == 0) {
; #pragma unroll
;                 for (int i = 0; i < 8; ++i) { const int g = LT() + NTHR * i; const LAS f32x4* XP = (const LAS f32x4*)(X + phys(4 * g)); KE4[2 * g] = XP[0]; KE4[2 * g + 1] = XP[1]; }
;                 __syncthreads();
;             }
	v_pk_add_f32 v[18:19], v[28:29], v[2:3]
	v_pk_add_f32 v[10:11], v[22:23], v[10:11] neg_lo:[0,1] neg_hi:[0,1]
	v_pk_add_f32 v[30:31], v[34:35], v[30:31] neg_lo:[0,1] neg_hi:[0,1]
	v_pk_add_f32 v[38:39], v[24:25], v[38:39] neg_lo:[0,1] neg_hi:[0,1]
	v_pk_add_f32 v[2:3], v[28:29], v[2:3] neg_lo:[0,1] neg_hi:[0,1]
	v_pk_add_f32 v[28:29], v[12:13], v[58:59] op_sel:[0,1] op_sel_hi:[1,0] neg_lo:[0,1]
	v_pk_add_f32 v[24:25], v[54:55], v[62:63] op_sel:[0,1] op_sel_hi:[1,0] neg_lo:[0,1]
	v_pk_add_f32 v[34:35], v[56:57], v[20:21] op_sel:[0,1] op_sel_hi:[1,0] neg_lo:[0,1]
	v_pk_add_f32 v[22:23], v[50:51], v[4:5] op_sel:[0,1] op_sel_hi:[1,0] neg_lo:[0,1]
	v_pk_add_f32 v[12:13], v[12:13], v[58:59] op_sel:[0,1] op_sel_hi:[1,0] neg_hi:[0,1]
	v_pk_add_f32 v[54:55], v[54:55], v[62:63] op_sel:[0,1] op_sel_hi:[1,0] neg_hi:[0,1]
	v_pk_add_f32 v[56:57], v[56:57], v[20:21] op_sel:[0,1] op_sel_hi:[1,0] neg_hi:[0,1]
	v_pk_add_f32 v[50:51], v[50:51], v[4:5] op_sel:[0,1] op_sel_hi:[1,0] neg_hi:[0,1]
	ds_write_b64 v151, v[32:33] offset:0
	ds_write_b64 v151, v[60:61] offset:8704
	ds_write_b64 v151, v[26:27] offset:17408
	ds_write_b64 v151, v[18:19] offset:26112
	ds_write_b64 v151, v[28:29] offset:34816
	ds_write_b64 v151, v[24:25] offset:43520
	ds_write_b64 v151, v[34:35] offset:52224
	ds_write_b64 v151, v[22:23] offset:60928
	ds_write_b64 v176, v[10:11] offset:0
	ds_write_b64 v176, v[30:31] offset:8704
	ds_write_b64 v176, v[38:39] offset:17408
	ds_write_b64 v176, v[2:3] offset:26112
	ds_write_b64 v176, v[12:13] offset:34816
	ds_write_b64 v176, v[54:55] offset:43520
	ds_write_b64 v176, v[56:57] offset:52224
	ds_write_b64 v176, v[50:51] offset:60928
	s_cbranch_scc1 .LBB0_856
	s_waitcnt lgkmcnt(0)
	s_barrier
	s_andn2_b64 vcc, exec, s[34:35]
	s_mov_b64 s[12:13], -1
	s_cbranch_vccnz .LBB0_662
	v_mov_b32_e32 v1, v140
	s_mov_b64 s[12:13], 0
	v_lshlrev_b32_e32 v0, 1, v1
	v_and_b32_e32 v2, 0xffffffe0, v0
	v_lshlrev_b32_e32 v1, 5, v1
	v_add3_u32 v4, 0, v2, v1
	v_ashrrev_i32_e32 v1, 31, v0
	v_lshl_add_u64 v[8:9], v[0:1], 4, s[18:19]
	ds_read_b128 v[0:3], v4
	ds_read_b128 v[4:7], v4 offset:16
	s_waitcnt lgkmcnt(1)
	global_store_dwordx4 v[8:9], v[0:3], off
	s_waitcnt lgkmcnt(0)
	global_store_dwordx4 v[8:9], v[4:7], off offset:16
	v_mov_b32_e32 v0, v140
	s_nop 0
	v_add_u32_e32 v1, 0x200, v0
	v_lshlrev_b32_e32 v0, 1, v1
	v_and_b32_e32 v2, 0xffffffe0, v0
	v_lshlrev_b32_e32 v1, 5, v1
	v_add3_u32 v4, 0, v2, v1
	v_ashrrev_i32_e32 v1, 31, v0
	v_lshl_add_u64 v[8:9], v[0:1], 4, s[18:19]
	ds_read_b128 v[0:3], v4
	ds_read_b128 v[4:7], v4 offset:16
	s_waitcnt lgkmcnt(1)
	global_store_dwordx4 v[8:9], v[0:3], off
	s_waitcnt lgkmcnt(0)
	global_store_dwordx4 v[8:9], v[4:7], off offset:16
	v_mov_b32_e32 v0, v140
	s_nop 0
	v_add_u32_e32 v1, 0x400, v0
	v_lshlrev_b32_e32 v0, 1, v1
	v_and_b32_e32 v2, 0xffffffe0, v0
	v_lshlrev_b32_e32 v1, 5, v1
	v_add3_u32 v4, 0, v2, v1
	v_ashrrev_i32_e32 v1, 31, v0
	v_lshl_add_u64 v[8:9], v[0:1], 4, s[18:19]
	ds_read_b128 v[0:3], v4
	ds_read_b128 v[4:7], v4 offset:16
	s_waitcnt lgkmcnt(1)
	global_store_dwordx4 v[8:9], v[0:3], off
	s_waitcnt lgkmcnt(0)
	global_store_dwordx4 v[8:9], v[4:7], off offset:16
	v_mov_b32_e32 v0, v140
	s_nop 0
	v_add_u32_e32 v1, 0x600, v0
	v_lshlrev_b32_e32 v0, 1, v1
	v_and_b32_e32 v2, 0xffffffe0, v0
	v_lshlrev_b32_e32 v1, 5, v1
	v_add3_u32 v4, 0, v2, v1
	v_ashrrev_i32_e32 v1, 31, v0
	v_lshl_add_u64 v[8:9], v[0:1], 4, s[18:19]
	ds_read_b128 v[0:3], v4
	ds_read_b128 v[4:7], v4 offset:16
	s_waitcnt lgkmcnt(1)
	global_store_dwordx4 v[8:9], v[0:3], off
	s_waitcnt lgkmcnt(0)
	global_store_dwordx4 v[8:9], v[4:7], off offset:16
	v_mov_b32_e32 v0, v140
	s_nop 0
	v_add_u32_e32 v1, 0x800, v0
	v_lshlrev_b32_e32 v0, 1, v1
	v_and_b32_e32 v2, 0xffffffe0, v0
	v_lshlrev_b32_e32 v1, 5, v1
	v_add3_u32 v4, 0, v2, v1
	v_ashrrev_i32_e32 v1, 31, v0
	v_lshl_add_u64 v[8:9], v[0:1], 4, s[18:19]
	ds_read_b128 v[0:3], v4
	ds_read_b128 v[4:7], v4 offset:16
	s_waitcnt lgkmcnt(1)
	global_store_dwordx4 v[8:9], v[0:3], off
	s_waitcnt lgkmcnt(0)
	global_store_dwordx4 v[8:9], v[4:7], off offset:16
	v_mov_b32_e32 v0, v140
	s_nop 0
	v_add_u32_e32 v1, 0xa00, v0
	v_lshlrev_b32_e32 v0, 1, v1
	v_and_b32_e32 v2, 0xffffffe0, v0
	v_lshlrev_b32_e32 v1, 5, v1
	v_add3_u32 v4, 0, v2, v1
	v_ashrrev_i32_e32 v1, 31, v0
	v_lshl_add_u64 v[8:9], v[0:1], 4, s[18:19]
	ds_read_b128 v[0:3], v4
	ds_read_b128 v[4:7], v4 offset:16
	s_waitcnt lgkmcnt(1)
	global_store_dwordx4 v[8:9], v[0:3], off
	s_waitcnt lgkmcnt(0)
	global_store_dwordx4 v[8:9], v[4:7], off offset:16
	v_mov_b32_e32 v0, v140
	s_nop 0
	v_add_u32_e32 v1, 0xc00, v0
	v_lshlrev_b32_e32 v0, 1, v1
	v_and_b32_e32 v2, 0xffffffe0, v0
	v_lshlrev_b32_e32 v1, 5, v1
	v_add3_u32 v4, 0, v2, v1
	v_ashrrev_i32_e32 v1, 31, v0
	v_lshl_add_u64 v[8:9], v[0:1], 4, s[18:19]
	ds_read_b128 v[0:3], v4
	ds_read_b128 v[4:7], v4 offset:16
	s_waitcnt lgkmcnt(1)
	global_store_dwordx4 v[8:9], v[0:3], off
	s_waitcnt lgkmcnt(0)
	global_store_dwordx4 v[8:9], v[4:7], off offset:16
	v_mov_b32_e32 v0, v140
	s_nop 0
	v_add_u32_e32 v1, 0xe00, v0
	v_lshlrev_b32_e32 v0, 1, v1
	v_and_b32_e32 v2, 0xffffffe0, v0
	v_lshlrev_b32_e32 v1, 5, v1
	v_add3_u32 v4, 0, v2, v1
	v_ashrrev_i32_e32 v1, 31, v0
	v_lshl_add_u64 v[8:9], v[0:1], 4, s[18:19]
	ds_read_b128 v[0:3], v4
	ds_read_b128 v[4:7], v4 offset:16
	s_waitcnt lgkmcnt(1)
	global_store_dwordx4 v[8:9], v[0:3], off
	s_waitcnt lgkmcnt(0)
	global_store_dwordx4 v[8:9], v[4:7], off offset:16
	s_nop 0
	s_branch .LBB0_662
